# all four GEMM K-loops: s_sleep 2 at the start of every load section (partner wave's MFMA section starts unimpeded)
# baseline (speedup 1.0000x reference)
; #define PG8_STAGE(bufoff, gbase, voff) do { _Pragma("unroll") for (int _i = 0; _i < 2; ++_i) \
;         __builtin_amdgcn_global_load_lds((const unsigned*)((const char*)(gbase) + (voff)[_i]), (LAS unsigned*)(lds + (bufoff) + ldsw + _i * 8192), 16, 0, 0); } while (0)
; #define PG8_LDA(dst, b, h) do { _Pragma("unroll") for (int m = 0; m < 4; ++m) _Pragma("unroll") for (int k = 0; k < 2; ++k) dst[m][k] = *(const LAS bf16x8*)(lds + PG8_SA(b, h) + aoff + m * 2048 + k * 1024); } while (0)
; #define PG8_LDB(dst, b, h) do { _Pragma("unroll") for (int n = 0; n < 2; ++n) _Pragma("unroll") for (int k = 0; k < 2; ++k) dst[n][k] = *(const LAS bf16x8*)(lds + PG8_SB(b, h) + boff + n * 2048 + k * 1024); } while (0)
; #define PG8_MMA(ai, bj, At, Bt) do { __builtin_amdgcn_s_setprio(1); _Pragma("unroll") for (int m = 0; m < 4; ++m) _Pragma("unroll") for (int n = 0; n < 2; ++n) _Pragma("unroll") for (int k = 0; k < 2; ++k) \
;         acc[ai][bj][m][n] = __builtin_amdgcn_mfma_f32_16x16x32_bf16(Bt[n][k], At[m][k], acc[ai][bj][m][n], 0, 0, 0); __builtin_amdgcn_s_setprio(0); } while (0)
; #define PG8_WAIT_V(n) asm volatile("s_waitcnt vmcnt(" #n ")" ::: "memory")
; #define PG8_WAIT_L(n) asm volatile("s_waitcnt lgkmcnt(" #n ")" ::: "memory")
; #define PG8_BAR __builtin_amdgcn_s_barrier()
; #define PG8_SCHED __builtin_amdgcn_sched_barrier(0)
; template <class Epi>
; __device__ __forceinline__ void gemm_phase(LAS unsigned char* lds, const Gemm g, const int G, const int cidx, const Epi& E) {
;     ...
;             const char* a1 = cA + (size_t)(t + 1) * kstep;
;             const char* a2 = last ? nA : cA + (size_t)(t + 2) * kstep; const char* b2 = last ? nB : cB + (size_t)(t + 2) * kstep;
;             const char* a3 = a2 + kstep; const char* b3 = b2 + kstep;
;             PG8_LDB(B0, 0, 0); PG8_LDB(B1, 0, 1); PG8_SCHED; PG8_LDA(At, 0, 0); PG8_STAGE(PG8_SA(1, 1), a1 + hstep, voffA);
;             PG8_WAIT_V(8); PG8_WAIT_L(0); PG8_BAR; PG8_MMA(0, 0, At, B0); PG8_MMA(0, 1, At, B1); PG8_BAR; PG8_SCHED;
;             PG8_LDA(At, 0, 1); PG8_STAGE(PG8_SB(0, 0), b2, voffB); PG8_STAGE(PG8_SB(0, 1), b2 + hstep, voffB); PG8_STAGE(PG8_SA(0, 0), a2, voffA);
;             PG8_WAIT_V(8); PG8_WAIT_L(0); PG8_BAR; PG8_MMA(1, 0, At, B0); PG8_MMA(1, 1, At, B1); PG8_BAR; PG8_SCHED;
.LBB0_82:
	s_add_u32 s26, s24, 0xfffc0080
	s_addc_u32 s27, s25, -1
	s_add_i32 s43, 0, 0x10000
	s_cmp_eq_u32 s45, 12
	s_cselect_b32 s29, s13, s27
	s_cselect_b32 s28, s17, s26
	s_cselect_b32 s27, s9, s44
	s_cselect_b32 s26, s22, s33
	s_add_i32 s68, 0, 0x14000
	v_add_u32_e32 v162, s43, v145
	v_add_u32_e32 v178, s68, v145
	ds_read_b128 v[132:135], v162
	ds_read_b128 v[140:143], v162 offset:1024
	ds_read_b128 v[156:159], v162 offset:2048
	ds_read_b128 v[162:165], v162 offset:3072
	ds_read_b128 v[166:169], v178
	ds_read_b128 v[170:173], v178 offset:1024
	ds_read_b128 v[174:177], v178 offset:2048
	ds_read_b128 v[178:181], v178 offset:3072
	v_lshl_add_u64 v[226:227], s[24:25], 0, v[154:155]
	s_add_i32 m0, s21, 0xc000
	ds_read_b128 v[182:185], v161
	ds_read_b128 v[186:189], v161 offset:1024
	ds_read_b128 v[190:193], v161 offset:2048
	ds_read_b128 v[194:197], v161 offset:3072
	ds_read_b128 v[198:201], v161 offset:4096
	ds_read_b128 v[214:217], v161 offset:5120
	ds_read_b128 v[218:221], v161 offset:6144
	ds_read_b128 v[222:225], v161 offset:7168
	global_load_lds_dwordx4 v[226:227], off
	v_lshl_add_u64 v[226:227], s[24:25], 0, v[152:153]
	s_add_i32 m0, s21, 0xe000
	s_nop 0
	global_load_lds_dwordx4 v[226:227], off
	s_waitcnt vmcnt(8)
	s_waitcnt lgkmcnt(0)
	s_barrier
	s_setprio 1
	s_waitcnt lgkmcnt(0)
	v_mfma_f32_16x16x32_bf16 v[128:131], v[132:135], v[182:185], v[128:131]
	v_mfma_f32_16x16x32_bf16 v[120:123], v[156:159], v[182:185], v[120:123]
	v_mfma_f32_16x16x32_bf16 v[112:115], v[132:135], v[190:193], v[112:115]
	v_mfma_f32_16x16x32_bf16 v[104:107], v[156:159], v[190:193], v[104:107]
	v_mfma_f32_16x16x32_bf16 v[96:99], v[132:135], v[198:201], v[96:99]
	v_mfma_f32_16x16x32_bf16 v[88:91], v[156:159], v[198:201], v[88:91]
	v_mfma_f32_16x16x32_bf16 v[80:83], v[132:135], v[218:221], v[80:83]
	v_mfma_f32_16x16x32_bf16 v[72:75], v[156:159], v[218:221], v[72:75]
	v_mfma_f32_16x16x32_bf16 v[128:131], v[140:143], v[186:189], v[128:131]
	v_mfma_f32_16x16x32_bf16 v[120:123], v[162:165], v[186:189], v[120:123]
	v_mfma_f32_16x16x32_bf16 v[112:115], v[140:143], v[194:197], v[112:115]
	v_mfma_f32_16x16x32_bf16 v[104:107], v[162:165], v[194:197], v[104:107]
	v_mfma_f32_16x16x32_bf16 v[96:99], v[140:143], v[214:217], v[96:99]
	v_mfma_f32_16x16x32_bf16 v[88:91], v[162:165], v[214:217], v[88:91]
	v_mfma_f32_16x16x32_bf16 v[80:83], v[140:143], v[222:225], v[80:83]
	v_mfma_f32_16x16x32_bf16 v[72:75], v[162:165], v[222:225], v[72:75]
	s_setprio 0
	s_setprio 1
	v_mfma_f32_16x16x32_bf16 v[124:127], v[166:169], v[182:185], v[124:127]
	v_mfma_f32_16x16x32_bf16 v[116:119], v[174:177], v[182:185], v[116:119]
	v_mfma_f32_16x16x32_bf16 v[108:111], v[166:169], v[190:193], v[108:111]
	v_mfma_f32_16x16x32_bf16 v[100:103], v[174:177], v[190:193], v[100:103]
	v_mfma_f32_16x16x32_bf16 v[92:95], v[166:169], v[198:201], v[92:95]
	v_mfma_f32_16x16x32_bf16 v[84:87], v[174:177], v[198:201], v[84:87]
	v_mfma_f32_16x16x32_bf16 v[76:79], v[166:169], v[218:221], v[76:79]
	v_mfma_f32_16x16x32_bf16 v[68:71], v[174:177], v[218:221], v[68:71]
	v_mfma_f32_16x16x32_bf16 v[124:127], v[170:173], v[186:189], v[124:127]
	v_mfma_f32_16x16x32_bf16 v[116:119], v[178:181], v[186:189], v[116:119]
	v_mfma_f32_16x16x32_bf16 v[108:111], v[170:173], v[194:197], v[108:111]
	v_mfma_f32_16x16x32_bf16 v[100:103], v[178:181], v[194:197], v[100:103]
	v_mfma_f32_16x16x32_bf16 v[92:95], v[170:173], v[214:217], v[92:95]
	v_mfma_f32_16x16x32_bf16 v[84:87], v[178:181], v[214:217], v[84:87]
	v_mfma_f32_16x16x32_bf16 v[76:79], v[170:173], v[222:225], v[76:79]
	v_mfma_f32_16x16x32_bf16 v[68:71], v[178:181], v[222:225], v[68:71]
	s_setprio 0
	s_barrier
	s_sleep 2
	s_add_i32 s43, s43, s36
	v_lshl_add_u64 v[226:227], s[26:27], 0, v[148:149]
	s_mov_b32 m0, s43
	ds_read_b128 v[182:185], v161 offset:16384
	ds_read_b128 v[186:189], v161 offset:17408
	ds_read_b128 v[190:193], v161 offset:18432
	ds_read_b128 v[194:197], v161 offset:19456
	ds_read_b128 v[198:201], v161 offset:20480
	ds_read_b128 v[214:217], v161 offset:21504
	ds_read_b128 v[218:221], v161 offset:22528
	ds_read_b128 v[222:225], v161 offset:23552
	global_load_lds_dwordx4 v[226:227], off
	s_add_i32 m0, s43, 0x2000
	s_add_u32 s76, s26, 0x40000
	v_lshl_add_u64 v[228:229], s[26:27], 0, v[0:1]
	s_addc_u32 s77, s27, 0
	s_add_i32 s43, s68, s36
	global_load_lds_dwordx4 v[228:229], off
	v_lshl_add_u64 v[230:231], s[76:77], 0, v[148:149]
	s_mov_b32 m0, s43
	v_lshl_add_u64 v[232:233], s[28:29], 0, v[146:147]
	global_load_lds_dwordx4 v[230:231], off
	v_lshl_add_u64 v[230:231], s[76:77], 0, v[0:1]
	s_add_i32 m0, s43, 0x2000
	s_nop 0
	global_load_lds_dwordx4 v[230:231], off
	v_lshl_add_u64 v[230:231], s[28:29], 0, v[150:151]
	s_mov_b32 m0, s21
	s_nop 0
	global_load_lds_dwordx4 v[230:231], off
	s_mov_b32 m0, s38
	s_nop 0
	global_load_lds_dwordx4 v[232:233], off
	s_waitcnt vmcnt(8)
	s_waitcnt lgkmcnt(0)
	s_barrier
; #define PG8_STAGE(bufoff, gbase, voff) do { _Pragma("unroll") for (int _i = 0; _i < 2; ++_i) \
;         __builtin_amdgcn_global_load_lds((const unsigned*)((const char*)(gbase) + (voff)[_i]), (LAS unsigned*)(lds + (bufoff) + ldsw + _i * 8192), 16, 0, 0); } while (0)
; #define PG8_LDA(dst, b, h) do { _Pragma("unroll") for (int m = 0; m < 4; ++m) _Pragma("unroll") for (int k = 0; k < 2; ++k) dst[m][k] = *(const LAS bf16x8*)(lds + PG8_SA(b, h) + aoff + m * 2048 + k * 1024); } while (0)
; #define PG8_LDB(dst, b, h) do { _Pragma("unroll") for (int n = 0; n < 2; ++n) _Pragma("unroll") for (int k = 0; k < 2; ++k) dst[n][k] = *(const LAS bf16x8*)(lds + PG8_SB(b, h) + boff + n * 2048 + k * 1024); } while (0)
; #define PG8_MMA(ai, bj, At, Bt) do { __builtin_amdgcn_s_setprio(1); _Pragma("unroll") for (int m = 0; m < 4; ++m) _Pragma("unroll") for (int n = 0; n < 2; ++n) _Pragma("unroll") for (int k = 0; k < 2; ++k) \
;         acc[ai][bj][m][n] = __builtin_amdgcn_mfma_f32_16x16x32_bf16(Bt[n][k], At[m][k], acc[ai][bj][m][n], 0, 0, 0); __builtin_amdgcn_s_setprio(0); } while (0)
; #define PG8_WAIT_V(n) asm volatile("s_waitcnt vmcnt(" #n ")" ::: "memory")
; #define PG8_WAIT_L(n) asm volatile("s_waitcnt lgkmcnt(" #n ")" ::: "memory")
; #define PG8_BAR __builtin_amdgcn_s_barrier()
; #define PG8_SCHED __builtin_amdgcn_sched_barrier(0)
; template <class Epi>
; __device__ __forceinline__ void gemm_phase(LAS unsigned char* lds, const Gemm g, const int G, const int cidx, const Epi& E) {
;     ...
;             PG8_WAIT_V(8); PG8_WAIT_L(0); PG8_BAR; PG8_MMA(1, 0, At, B0); PG8_MMA(1, 1, At, B1); PG8_BAR; PG8_SCHED;
;             PG8_LDB(B0, 1, 0); PG8_LDB(B1, 1, 1); PG8_SCHED; PG8_LDA(At, 1, 0); PG8_STAGE(PG8_SA(0, 1), a2 + hstep, voffA);
;             PG8_WAIT_V(8); PG8_WAIT_L(0); PG8_BAR; PG8_MMA(0, 0, At, B0); PG8_MMA(0, 1, At, B1); PG8_BAR; PG8_SCHED;
	s_setprio 1
	s_waitcnt lgkmcnt(0)
	v_mfma_f32_16x16x32_bf16 v[64:67], v[132:135], v[182:185], v[64:67]
	v_mfma_f32_16x16x32_bf16 v[56:59], v[156:159], v[182:185], v[56:59]
	v_mfma_f32_16x16x32_bf16 v[48:51], v[132:135], v[190:193], v[48:51]
	v_mfma_f32_16x16x32_bf16 v[40:43], v[156:159], v[190:193], v[40:43]
	v_mfma_f32_16x16x32_bf16 v[32:35], v[132:135], v[198:201], v[32:35]
	v_mfma_f32_16x16x32_bf16 v[24:27], v[156:159], v[198:201], v[24:27]
	v_mfma_f32_16x16x32_bf16 v[16:19], v[132:135], v[218:221], v[16:19]
	v_mfma_f32_16x16x32_bf16 v[8:11], v[156:159], v[218:221], v[8:11]
	v_mfma_f32_16x16x32_bf16 v[64:67], v[140:143], v[186:189], v[64:67]
	v_mfma_f32_16x16x32_bf16 v[56:59], v[162:165], v[186:189], v[56:59]
	v_mfma_f32_16x16x32_bf16 v[48:51], v[140:143], v[194:197], v[48:51]
	v_mfma_f32_16x16x32_bf16 v[40:43], v[162:165], v[194:197], v[40:43]
	v_mfma_f32_16x16x32_bf16 v[32:35], v[140:143], v[214:217], v[32:35]
	v_mfma_f32_16x16x32_bf16 v[24:27], v[162:165], v[214:217], v[24:27]
	v_mfma_f32_16x16x32_bf16 v[16:19], v[140:143], v[222:225], v[16:19]
	v_mfma_f32_16x16x32_bf16 v[8:11], v[162:165], v[222:225], v[8:11]
	s_setprio 0
	s_setprio 1
	v_mfma_f32_16x16x32_bf16 v[60:63], v[166:169], v[182:185], v[60:63]
	v_mfma_f32_16x16x32_bf16 v[52:55], v[174:177], v[182:185], v[52:55]
	v_mfma_f32_16x16x32_bf16 v[44:47], v[166:169], v[190:193], v[44:47]
	v_mfma_f32_16x16x32_bf16 v[36:39], v[174:177], v[190:193], v[36:39]
	v_mfma_f32_16x16x32_bf16 v[28:31], v[166:169], v[198:201], v[28:31]
	v_mfma_f32_16x16x32_bf16 v[20:23], v[174:177], v[198:201], v[20:23]
	v_mfma_f32_16x16x32_bf16 v[12:15], v[166:169], v[218:221], v[12:15]
	v_mfma_f32_16x16x32_bf16 v[4:7], v[174:177], v[218:221], v[4:7]
	v_mfma_f32_16x16x32_bf16 v[60:63], v[170:173], v[186:189], v[60:63]
	v_mfma_f32_16x16x32_bf16 v[52:55], v[178:181], v[186:189], v[52:55]
	v_mfma_f32_16x16x32_bf16 v[44:47], v[170:173], v[194:197], v[44:47]
	v_mfma_f32_16x16x32_bf16 v[36:39], v[178:181], v[194:197], v[36:39]
	v_mfma_f32_16x16x32_bf16 v[28:31], v[170:173], v[214:217], v[28:31]
	v_mfma_f32_16x16x32_bf16 v[20:23], v[178:181], v[214:217], v[20:23]
	v_mfma_f32_16x16x32_bf16 v[12:15], v[170:173], v[222:225], v[12:15]
	v_mfma_f32_16x16x32_bf16 v[4:7], v[178:181], v[222:225], v[4:7]
	s_setprio 0
	s_barrier
	s_sleep 2
	s_add_i32 s43, 0, 0x18000
	s_add_i32 s68, 0, 0x1c000
	v_add_u32_e32 v162, s43, v145
	v_add_u32_e32 v178, s68, v145
	ds_read_b128 v[132:135], v162
	ds_read_b128 v[140:143], v162 offset:1024
	ds_read_b128 v[156:159], v162 offset:2048
	ds_read_b128 v[162:165], v162 offset:3072
	ds_read_b128 v[166:169], v178
	ds_read_b128 v[170:173], v178 offset:1024
	ds_read_b128 v[174:177], v178 offset:2048
	ds_read_b128 v[178:181], v178 offset:3072
	s_add_u32 s28, s28, 0x40000
	s_addc_u32 s29, s29, 0
	s_mov_b32 m0, s39
	v_lshl_add_u64 v[234:235], s[28:29], 0, v[150:151]
	ds_read_b128 v[182:185], v161 offset:32768
	ds_read_b128 v[186:189], v161 offset:33792
	ds_read_b128 v[190:193], v161 offset:34816
	ds_read_b128 v[194:197], v161 offset:35840
	ds_read_b128 v[198:201], v161 offset:36864
	ds_read_b128 v[214:217], v161 offset:37888
	ds_read_b128 v[218:221], v161 offset:38912
	ds_read_b128 v[222:225], v161 offset:39936
	global_load_lds_dwordx4 v[234:235], off
	v_lshl_add_u64 v[234:235], s[28:29], 0, v[146:147]
	s_mov_b32 m0, s75
	s_nop 0
	global_load_lds_dwordx4 v[234:235], off
	s_waitcnt vmcnt(8)
	s_waitcnt lgkmcnt(0)
	s_barrier
	s_setprio 1
	s_waitcnt lgkmcnt(0)
	v_mfma_f32_16x16x32_bf16 v[128:131], v[132:135], v[182:185], v[128:131]
	v_mfma_f32_16x16x32_bf16 v[120:123], v[156:159], v[182:185], v[120:123]
	v_mfma_f32_16x16x32_bf16 v[112:115], v[132:135], v[190:193], v[112:115]
	v_mfma_f32_16x16x32_bf16 v[104:107], v[156:159], v[190:193], v[104:107]
	v_mfma_f32_16x16x32_bf16 v[96:99], v[132:135], v[198:201], v[96:99]
	v_mfma_f32_16x16x32_bf16 v[88:91], v[156:159], v[198:201], v[88:91]
	v_mfma_f32_16x16x32_bf16 v[80:83], v[132:135], v[218:221], v[80:83]
	v_mfma_f32_16x16x32_bf16 v[72:75], v[156:159], v[218:221], v[72:75]
	v_mfma_f32_16x16x32_bf16 v[128:131], v[140:143], v[186:189], v[128:131]
	v_mfma_f32_16x16x32_bf16 v[120:123], v[162:165], v[186:189], v[120:123]
	v_mfma_f32_16x16x32_bf16 v[112:115], v[140:143], v[194:197], v[112:115]
	v_mfma_f32_16x16x32_bf16 v[104:107], v[162:165], v[194:197], v[104:107]
	v_mfma_f32_16x16x32_bf16 v[96:99], v[140:143], v[214:217], v[96:99]
	v_mfma_f32_16x16x32_bf16 v[88:91], v[162:165], v[214:217], v[88:91]
	v_mfma_f32_16x16x32_bf16 v[80:83], v[140:143], v[222:225], v[80:83]
	v_mfma_f32_16x16x32_bf16 v[72:75], v[162:165], v[222:225], v[72:75]
	s_setprio 0
	s_setprio 1
	v_mfma_f32_16x16x32_bf16 v[124:127], v[166:169], v[182:185], v[124:127]
	v_mfma_f32_16x16x32_bf16 v[116:119], v[174:177], v[182:185], v[116:119]
	v_mfma_f32_16x16x32_bf16 v[108:111], v[166:169], v[190:193], v[108:111]
	v_mfma_f32_16x16x32_bf16 v[100:103], v[174:177], v[190:193], v[100:103]
	v_mfma_f32_16x16x32_bf16 v[92:95], v[166:169], v[198:201], v[92:95]
	v_mfma_f32_16x16x32_bf16 v[84:87], v[174:177], v[198:201], v[84:87]
	v_mfma_f32_16x16x32_bf16 v[76:79], v[166:169], v[218:221], v[76:79]
	v_mfma_f32_16x16x32_bf16 v[68:71], v[174:177], v[218:221], v[68:71]
	v_mfma_f32_16x16x32_bf16 v[124:127], v[170:173], v[186:189], v[124:127]
	v_mfma_f32_16x16x32_bf16 v[116:119], v[178:181], v[186:189], v[116:119]
	v_mfma_f32_16x16x32_bf16 v[108:111], v[170:173], v[194:197], v[108:111]
	v_mfma_f32_16x16x32_bf16 v[100:103], v[178:181], v[194:197], v[100:103]
	v_mfma_f32_16x16x32_bf16 v[92:95], v[170:173], v[214:217], v[92:95]
	v_mfma_f32_16x16x32_bf16 v[84:87], v[178:181], v[214:217], v[84:87]
	v_mfma_f32_16x16x32_bf16 v[76:79], v[170:173], v[222:225], v[76:79]
	v_mfma_f32_16x16x32_bf16 v[68:71], v[178:181], v[222:225], v[68:71]
	s_setprio 0
	s_barrier
; __device__ __forceinline__ unsigned pk2(float lo, float hi) { unsigned r; asm("v_cvt_pk_bf16_f32 %0, %1, %2" : "=v"(r) : "v"(lo), "v"(hi)); return r; }
; __device__ __forceinline__ float silu(float x) { return x * sigm(x); }
; #define PG8_STAGE(bufoff, gbase, voff) do { _Pragma("unroll") for (int _i = 0; _i < 2; ++_i) \
;         __builtin_amdgcn_global_load_lds((const unsigned*)((const char*)(gbase) + (voff)[_i]), (LAS unsigned*)(lds + (bufoff) + ldsw + _i * 8192), 16, 0, 0); } while (0)
; #define PG8_LDA(dst, b, h) do { _Pragma("unroll") for (int m = 0; m < 4; ++m) _Pragma("unroll") for (int k = 0; k < 2; ++k) dst[m][k] = *(const LAS bf16x8*)(lds + PG8_SA(b, h) + aoff + m * 2048 + k * 1024); } while (0)
; #define PG8_WAIT_V(n) asm volatile("s_waitcnt vmcnt(" #n ")" ::: "memory")
; #define PG8_WAIT_L(n) asm volatile("s_waitcnt lgkmcnt(" #n ")" ::: "memory")
; #define PG8_BAR __builtin_amdgcn_s_barrier()
; #define PG8_SCHED __builtin_amdgcn_sched_barrier(0)
;     __device__ __forceinline__ void operator()(const f32x4 (&acc)[2][2][4][2], const Unit& u, int wr, int wc, int fr, int fq) const {
;         const int row0 = u.pm * BM + wr * 64 + fr, col0 = u.pn * HALF + wc * 32 + 8 * fq;
; #pragma unroll
;         for (int ai = 0; ai < 2; ++ai)
; #pragma unroll
;             for (int m = 0; m < 4; ++m) { bf16_t* rowp = O + (size_t)(row0 + ai * HALF + m * 16) * ldc + col0;
;                 const f32x4 g0 = acc[ai][0][m][0], g1 = acc[ai][0][m][1], u0 = acc[ai][1][m][0], u1 = acc[ai][1][m][1];
;                 u32x4 w; w.x = pk2(silu(g0[0]) * u0[0], silu(g0[1]) * u0[1]); w.y = pk2(silu(g0[2]) * u0[2], silu(g0[3]) * u0[3]);
;                 w.z = pk2(silu(g1[0]) * u1[0], silu(g1[1]) * u1[1]); w.w = pk2(silu(g1[2]) * u1[2], silu(g1[3]) * u1[3]);
;                 *(u32x4*)rowp = w; }
; template <class Epi>
; __device__ __forceinline__ void gemm_phase(LAS unsigned char* lds, const Gemm g, const int G, const int cidx, const Epi& E) {
;     ...
;             PG8_LDA(At, 1, 1); PG8_STAGE(PG8_SB(1, 0), b3, voffB); PG8_STAGE(PG8_SB(1, 1), b3 + hstep, voffB); PG8_STAGE(PG8_SA(1, 0), a3, voffA);
;             PG8_WAIT_V(8); PG8_WAIT_L(0); PG8_BAR; PG8_MMA(1, 0, At, B0); PG8_MMA(1, 1, At, B1); PG8_BAR; PG8_SCHED;
;         }
;         if constexpr (!Epi::AFTER_DRAIN) E(acc, cur, wr, wc, fr, fq);
	s_sleep 2
	s_add_i32 s28, s43, s36
	v_lshl_add_u64 v[226:227], v[226:227], 0, s[46:47]
	s_mov_b32 m0, s28
	ds_read_b128 v[182:185], v161 offset:49152
	ds_read_b128 v[186:189], v161 offset:50176
	ds_read_b128 v[190:193], v161 offset:51200
	ds_read_b128 v[194:197], v161 offset:52224
	ds_read_b128 v[198:201], v161 offset:53248
	ds_read_b128 v[214:217], v161 offset:54272
	ds_read_b128 v[218:221], v161 offset:55296
	ds_read_b128 v[222:225], v161 offset:56320
	global_load_lds_dwordx4 v[226:227], off
	s_add_i32 m0, s28, 0x2000
	s_add_u32 s26, s26, 0x40080
	v_lshl_add_u64 v[226:227], v[228:229], 0, s[46:47]
	s_addc_u32 s27, s27, 0
	s_add_i32 s28, s68, s36
	global_load_lds_dwordx4 v[226:227], off
	v_lshl_add_u64 v[226:227], s[26:27], 0, v[148:149]
	s_mov_b32 m0, s28
	s_nop 0
	global_load_lds_dwordx4 v[226:227], off
	v_lshl_add_u64 v[226:227], s[26:27], 0, v[0:1]
	s_add_i32 m0, s28, 0x2000
	s_nop 0
	global_load_lds_dwordx4 v[226:227], off
	v_lshl_add_u64 v[226:227], v[230:231], 0, s[46:47]
	s_mov_b32 m0, s79
	s_nop 0
	global_load_lds_dwordx4 v[226:227], off
	v_lshl_add_u64 v[226:227], v[232:233], 0, s[46:47]
	s_mov_b32 m0, s34
	s_nop 0
	global_load_lds_dwordx4 v[226:227], off
	s_waitcnt vmcnt(8)
	s_waitcnt lgkmcnt(0)
	s_barrier
	s_setprio 1
	s_waitcnt lgkmcnt(0)
	v_mfma_f32_16x16x32_bf16 v[64:67], v[132:135], v[182:185], v[64:67]
	v_mfma_f32_16x16x32_bf16 v[56:59], v[156:159], v[182:185], v[56:59]
	v_mfma_f32_16x16x32_bf16 v[48:51], v[132:135], v[190:193], v[48:51]
	v_mfma_f32_16x16x32_bf16 v[40:43], v[156:159], v[190:193], v[40:43]
	v_mfma_f32_16x16x32_bf16 v[32:35], v[132:135], v[198:201], v[32:35]
	v_mfma_f32_16x16x32_bf16 v[24:27], v[156:159], v[198:201], v[24:27]
	v_mfma_f32_16x16x32_bf16 v[16:19], v[132:135], v[218:221], v[16:19]
	v_mfma_f32_16x16x32_bf16 v[8:11], v[156:159], v[218:221], v[8:11]
	v_mfma_f32_16x16x32_bf16 v[64:67], v[140:143], v[186:189], v[64:67]
	v_mfma_f32_16x16x32_bf16 v[56:59], v[162:165], v[186:189], v[56:59]
	v_mfma_f32_16x16x32_bf16 v[48:51], v[140:143], v[194:197], v[48:51]
	v_mfma_f32_16x16x32_bf16 v[40:43], v[162:165], v[194:197], v[40:43]
	v_mfma_f32_16x16x32_bf16 v[32:35], v[140:143], v[214:217], v[32:35]
	v_mfma_f32_16x16x32_bf16 v[24:27], v[162:165], v[214:217], v[24:27]
	v_mfma_f32_16x16x32_bf16 v[16:19], v[140:143], v[222:225], v[16:19]
	v_mfma_f32_16x16x32_bf16 v[8:11], v[162:165], v[222:225], v[8:11]
	s_setprio 0
	s_setprio 1
	v_mfma_f32_16x16x32_bf16 v[60:63], v[166:169], v[182:185], v[60:63]
	v_mfma_f32_16x16x32_bf16 v[52:55], v[174:177], v[182:185], v[52:55]
	v_mfma_f32_16x16x32_bf16 v[44:47], v[166:169], v[190:193], v[44:47]
	v_mfma_f32_16x16x32_bf16 v[36:39], v[174:177], v[190:193], v[36:39]
	v_mfma_f32_16x16x32_bf16 v[28:31], v[166:169], v[198:201], v[28:31]
	v_mfma_f32_16x16x32_bf16 v[20:23], v[174:177], v[198:201], v[20:23]
	v_mfma_f32_16x16x32_bf16 v[12:15], v[166:169], v[218:221], v[12:15]
	v_mfma_f32_16x16x32_bf16 v[4:7], v[174:177], v[218:221], v[4:7]
	v_mfma_f32_16x16x32_bf16 v[60:63], v[170:173], v[186:189], v[60:63]
	v_mfma_f32_16x16x32_bf16 v[52:55], v[178:181], v[186:189], v[52:55]
	v_mfma_f32_16x16x32_bf16 v[44:47], v[170:173], v[194:197], v[44:47]
	v_mfma_f32_16x16x32_bf16 v[36:39], v[178:181], v[194:197], v[36:39]
	v_mfma_f32_16x16x32_bf16 v[28:31], v[170:173], v[214:217], v[28:31]
	v_mfma_f32_16x16x32_bf16 v[20:23], v[178:181], v[214:217], v[20:23]
	v_mfma_f32_16x16x32_bf16 v[12:15], v[170:173], v[222:225], v[12:15]
	v_mfma_f32_16x16x32_bf16 v[4:7], v[178:181], v[222:225], v[4:7]
	s_setprio 0
	s_barrier
	s_sleep 2
	s_add_i32 s45, s45, 2
	s_add_u32 s33, s33, 0x100
	s_addc_u32 s44, s44, 0
	s_add_u32 s24, s24, 0x100
	s_addc_u32 s25, s25, 0
	s_cmp_gt_u32 s45, 13
	s_cbranch_scc0 .LBB0_82
	v_lshl_or_b32 v132, s16, 7, v160
	v_lshl_add_u32 v162, s20, 8, v3
	v_ashrrev_i32_e32 v133, 31, v132
	v_mov_b64_e32 v[156:157], s[6:7]
	s_movk_i32 s9, 0x1600
	v_mad_i64_i32 v[134:135], s[16:17], v162, s9, v[156:157]
	v_lshlrev_b64 v[158:159], 1, v[132:133]
	v_lshl_add_u64 v[132:133], v[134:135], 0, v[158:159]
	v_mul_f32_e32 v134, 0xbfb8aa3b, v128
	v_exp_f32_e32 v134, v134
	s_and_b64 vcc, exec, s[4:5]
	s_mov_b32 s20, s12
	s_mov_b64 s[24:25], s[18:19]
	v_add_f32_e32 v134, 1.0, v134
	v_rcp_f32_e32 v134, v134
	s_mov_b64 s[26:27], s[14:15]
	v_mul_f32_e32 v128, v128, v134
	v_mul_f32_e32 v124, v128, v124
	v_mul_f32_e32 v128, 0xbfb8aa3b, v129
	v_exp_f32_e32 v128, v128
	s_nop 0
	v_add_f32_e32 v128, 1.0, v128
	v_rcp_f32_e32 v128, v128
	s_nop 0
	v_mul_f32_e32 v128, v129, v128
	v_mul_f32_e32 v125, v128, v125
	v_cvt_pk_bf16_f32 v124, v124, v125
	v_mul_f32_e32 v125, 0xbfb8aa3b, v130
	v_exp_f32_e32 v125, v125
	s_nop 0
	v_add_f32_e32 v125, 1.0, v125
	v_rcp_f32_e32 v125, v125
	s_nop 0
	v_mul_f32_e32 v125, v130, v125
	v_mul_f32_e32 v125, v125, v126
	v_mul_f32_e32 v126, 0xbfb8aa3b, v131
	v_exp_f32_e32 v126, v126
	s_nop 0
	v_add_f32_e32 v126, 1.0, v126
	v_rcp_f32_e32 v126, v126
	s_nop 0
	v_mul_f32_e32 v126, v131, v126
	v_mul_f32_e32 v126, v126, v127
	v_cvt_pk_bf16_f32 v125, v125, v126
	v_mul_f32_e32 v126, 0xbfb8aa3b, v120
	v_exp_f32_e32 v126, v126
	s_nop 0
	v_add_f32_e32 v126, 1.0, v126
	v_rcp_f32_e32 v126, v126
	s_nop 0
	v_mul_f32_e32 v120, v120, v126
	v_mul_f32_e32 v116, v120, v116
	v_mul_f32_e32 v120, 0xbfb8aa3b, v121
	v_exp_f32_e32 v120, v120
	s_nop 0
	v_add_f32_e32 v120, 1.0, v120
	v_rcp_f32_e32 v120, v120
	s_nop 0
	v_mul_f32_e32 v120, v121, v120
	v_mul_f32_e32 v117, v120, v117
	v_cvt_pk_bf16_f32 v126, v116, v117
	v_mul_f32_e32 v116, 0xbfb8aa3b, v122
	v_exp_f32_e32 v116, v116
	v_mul_f32_e32 v117, 0xbfb8aa3b, v123
	v_exp_f32_e32 v117, v117
	v_add_f32_e32 v116, 1.0, v116
	v_rcp_f32_e32 v116, v116
	v_add_f32_e32 v117, 1.0, v117
; __device__ __forceinline__ unsigned pk2(float lo, float hi) { unsigned r; asm("v_cvt_pk_bf16_f32 %0, %1, %2" : "=v"(r) : "v"(lo), "v"(hi)); return r; }
; __device__ __forceinline__ float silu(float x) { return x * sigm(x); }
;     __device__ __forceinline__ void operator()(const f32x4 (&acc)[2][2][4][2], const Unit& u, int wr, int wc, int fr, int fq) const {
;         const int row0 = u.pm * BM + wr * 64 + fr, col0 = u.pn * HALF + wc * 32 + 8 * fq;
; #pragma unroll
;         for (int ai = 0; ai < 2; ++ai)
; #pragma unroll
;             for (int m = 0; m < 4; ++m) { bf16_t* rowp = O + (size_t)(row0 + ai * HALF + m * 16) * ldc + col0;
;                 const f32x4 g0 = acc[ai][0][m][0], g1 = acc[ai][0][m][1], u0 = acc[ai][1][m][0], u1 = acc[ai][1][m][1];
;                 u32x4 w; w.x = pk2(silu(g0[0]) * u0[0], silu(g0[1]) * u0[1]); w.y = pk2(silu(g0[2]) * u0[2], silu(g0[3]) * u0[3]);
;                 w.z = pk2(silu(g1[0]) * u1[0], silu(g1[1]) * u1[1]); w.w = pk2(silu(g1[2]) * u1[2], silu(g1[3]) * u1[3]);
;                 *(u32x4*)rowp = w; }
	v_rcp_f32_e32 v117, v117
	v_mul_f32_e32 v116, v122, v116
	v_mul_f32_e32 v116, v116, v118
	v_mul_f32_e32 v118, 0xbfb8aa3b, v112
	v_exp_f32_e32 v118, v118
	v_mul_f32_e32 v117, v123, v117
	v_mul_f32_e32 v117, v117, v119
	v_cvt_pk_bf16_f32 v127, v116, v117
	v_add_f32_e32 v118, 1.0, v118
	v_rcp_f32_e32 v118, v118
	v_or_b32_e32 v116, 16, v162
	v_mad_i64_i32 v[116:117], s[16:17], v116, s9, v[156:157]
	v_mul_f32_e32 v112, v112, v118
	v_mul_f32_e32 v108, v112, v108
	v_mul_f32_e32 v112, 0xbfb8aa3b, v113
	v_exp_f32_e32 v112, v112
	v_lshl_add_u64 v[116:117], v[116:117], 0, v[158:159]
	global_store_dwordx4 v[132:133], v[124:127], off
	v_add_f32_e32 v112, 1.0, v112
	v_rcp_f32_e32 v112, v112
	s_nop 0
	v_mul_f32_e32 v112, v113, v112
	v_mul_f32_e32 v109, v112, v109
	v_cvt_pk_bf16_f32 v108, v108, v109
	v_mul_f32_e32 v109, 0xbfb8aa3b, v114
	v_exp_f32_e32 v109, v109
	s_nop 0
	v_add_f32_e32 v109, 1.0, v109
	v_rcp_f32_e32 v109, v109
	s_nop 0
	v_mul_f32_e32 v109, v114, v109
	v_mul_f32_e32 v109, v109, v110
	v_mul_f32_e32 v110, 0xbfb8aa3b, v115
	v_exp_f32_e32 v110, v110
	s_nop 0
	v_add_f32_e32 v110, 1.0, v110
	v_rcp_f32_e32 v110, v110
	s_nop 0
	v_mul_f32_e32 v110, v115, v110
	v_mul_f32_e32 v110, v110, v111
	v_cvt_pk_bf16_f32 v109, v109, v110
	v_mul_f32_e32 v110, 0xbfb8aa3b, v104
	v_exp_f32_e32 v110, v110
	s_nop 0
	v_add_f32_e32 v110, 1.0, v110
	v_rcp_f32_e32 v110, v110
	s_nop 0
	v_mul_f32_e32 v104, v104, v110
	v_mul_f32_e32 v100, v104, v100
	v_mul_f32_e32 v104, 0xbfb8aa3b, v105
	v_exp_f32_e32 v104, v104
	s_nop 0
	v_add_f32_e32 v104, 1.0, v104
	v_rcp_f32_e32 v104, v104
	s_nop 0
	v_mul_f32_e32 v104, v105, v104
	v_mul_f32_e32 v101, v104, v101
	v_cvt_pk_bf16_f32 v110, v100, v101
	v_mul_f32_e32 v100, 0xbfb8aa3b, v106
	v_exp_f32_e32 v100, v100
	v_mul_f32_e32 v101, 0xbfb8aa3b, v107
	v_exp_f32_e32 v101, v101
	v_add_f32_e32 v100, 1.0, v100
	v_rcp_f32_e32 v100, v100
	v_add_f32_e32 v101, 1.0, v101
	v_rcp_f32_e32 v101, v101
	v_mul_f32_e32 v100, v106, v100
	v_mul_f32_e32 v100, v100, v102
	v_mul_f32_e32 v102, 0xbfb8aa3b, v96
	v_exp_f32_e32 v102, v102
	v_mul_f32_e32 v101, v107, v101
	v_mul_f32_e32 v101, v101, v103
	v_cvt_pk_bf16_f32 v111, v100, v101
	v_add_f32_e32 v102, 1.0, v102
	v_rcp_f32_e32 v102, v102
	v_or_b32_e32 v100, 32, v162
	v_mad_i64_i32 v[100:101], s[16:17], v100, s9, v[156:157]
	v_mul_f32_e32 v96, v96, v102
	v_mul_f32_e32 v92, v96, v92
	v_mul_f32_e32 v96, 0xbfb8aa3b, v97
	v_exp_f32_e32 v96, v96
	v_lshl_add_u64 v[100:101], v[100:101], 0, v[158:159]
	global_store_dwordx4 v[116:117], v[108:111], off
	v_add_f32_e32 v96, 1.0, v96
	v_rcp_f32_e32 v96, v96
	s_nop 0
	v_mul_f32_e32 v96, v97, v96
	v_mul_f32_e32 v93, v96, v93
	v_cvt_pk_bf16_f32 v92, v92, v93
	v_mul_f32_e32 v93, 0xbfb8aa3b, v98
	v_exp_f32_e32 v93, v93
	s_nop 0
	v_add_f32_e32 v93, 1.0, v93
	v_rcp_f32_e32 v93, v93
	s_nop 0
	v_mul_f32_e32 v93, v98, v93
	v_mul_f32_e32 v93, v93, v94
	v_mul_f32_e32 v94, 0xbfb8aa3b, v99
	v_exp_f32_e32 v94, v94
	s_nop 0
	v_add_f32_e32 v94, 1.0, v94
	v_rcp_f32_e32 v94, v94
	s_nop 0
	v_mul_f32_e32 v94, v99, v94
	v_mul_f32_e32 v94, v94, v95
	v_cvt_pk_bf16_f32 v93, v93, v94
	v_mul_f32_e32 v94, 0xbfb8aa3b, v88
	v_exp_f32_e32 v94, v94
	s_nop 0
	v_add_f32_e32 v94, 1.0, v94
	v_rcp_f32_e32 v94, v94
	s_nop 0
	v_mul_f32_e32 v88, v88, v94
	v_mul_f32_e32 v84, v88, v84
	v_mul_f32_e32 v88, 0xbfb8aa3b, v89
	v_exp_f32_e32 v88, v88
	s_nop 0
	v_add_f32_e32 v88, 1.0, v88
	v_rcp_f32_e32 v88, v88
	s_nop 0
	v_mul_f32_e32 v88, v89, v88
	v_mul_f32_e32 v85, v88, v85
	v_cvt_pk_bf16_f32 v94, v84, v85
	v_mul_f32_e32 v84, 0xbfb8aa3b, v90
	v_exp_f32_e32 v84, v84
	v_mul_f32_e32 v85, 0xbfb8aa3b, v91
	v_exp_f32_e32 v85, v85
	v_add_f32_e32 v84, 1.0, v84
	v_rcp_f32_e32 v84, v84
	v_add_f32_e32 v85, 1.0, v85
	v_rcp_f32_e32 v85, v85
	v_mul_f32_e32 v84, v90, v84
	v_mul_f32_e32 v84, v84, v86
	v_mul_f32_e32 v86, 0xbfb8aa3b, v80
	v_exp_f32_e32 v86, v86
	v_mul_f32_e32 v85, v91, v85
	v_mul_f32_e32 v85, v85, v87
	v_cvt_pk_bf16_f32 v95, v84, v85
	v_add_f32_e32 v86, 1.0, v86
	v_rcp_f32_e32 v86, v86
	v_or_b32_e32 v84, 48, v162
	v_mad_i64_i32 v[84:85], s[16:17], v84, s9, v[156:157]
	v_mul_f32_e32 v80, v80, v86
	v_mul_f32_e32 v76, v80, v76
	v_mul_f32_e32 v80, 0xbfb8aa3b, v81
	v_exp_f32_e32 v80, v80
	v_lshl_add_u64 v[84:85], v[84:85], 0, v[158:159]
	global_store_dwordx4 v[100:101], v[92:95], off
	v_add_f32_e32 v80, 1.0, v80
	v_rcp_f32_e32 v80, v80
	s_nop 0
	v_mul_f32_e32 v80, v81, v80
	v_mul_f32_e32 v77, v80, v77
	v_cvt_pk_bf16_f32 v76, v76, v77
	v_mul_f32_e32 v77, 0xbfb8aa3b, v82
	v_exp_f32_e32 v77, v77
	s_nop 0
	v_add_f32_e32 v77, 1.0, v77
	v_rcp_f32_e32 v77, v77
	s_nop 0
	v_mul_f32_e32 v77, v82, v77
	v_mul_f32_e32 v77, v77, v78
	v_mul_f32_e32 v78, 0xbfb8aa3b, v83
	v_exp_f32_e32 v78, v78
	s_nop 0
	v_add_f32_e32 v78, 1.0, v78
	v_rcp_f32_e32 v78, v78
	s_nop 0
	v_mul_f32_e32 v78, v83, v78
	v_mul_f32_e32 v78, v78, v79
	v_cvt_pk_bf16_f32 v77, v77, v78
	v_mul_f32_e32 v78, 0xbfb8aa3b, v72
	v_exp_f32_e32 v78, v78
	s_nop 0
	v_add_f32_e32 v78, 1.0, v78
	v_rcp_f32_e32 v78, v78
	s_nop 0
	v_mul_f32_e32 v72, v72, v78
	v_mul_f32_e32 v68, v72, v68
	v_mul_f32_e32 v72, 0xbfb8aa3b, v73
	v_exp_f32_e32 v72, v72
	s_nop 0
	v_add_f32_e32 v72, 1.0, v72
	v_rcp_f32_e32 v72, v72
	s_nop 0
	v_mul_f32_e32 v72, v73, v72
	v_mul_f32_e32 v69, v72, v69
	v_cvt_pk_bf16_f32 v78, v68, v69
	v_mul_f32_e32 v68, 0xbfb8aa3b, v74
	v_exp_f32_e32 v68, v68
	v_mul_f32_e32 v69, 0xbfb8aa3b, v75
	v_exp_f32_e32 v69, v69
	v_add_f32_e32 v68, 1.0, v68
	v_rcp_f32_e32 v68, v68
	v_add_f32_e32 v69, 1.0, v69
	v_rcp_f32_e32 v69, v69
	v_mul_f32_e32 v68, v74, v68
	v_mul_f32_e32 v68, v68, v70
	v_mul_f32_e32 v70, 0xbfb8aa3b, v64
	v_exp_f32_e32 v70, v70
	v_mul_f32_e32 v69, v75, v69
; __device__ __forceinline__ unsigned pk2(float lo, float hi) { unsigned r; asm("v_cvt_pk_bf16_f32 %0, %1, %2" : "=v"(r) : "v"(lo), "v"(hi)); return r; }
; __device__ __forceinline__ float silu(float x) { return x * sigm(x); }
;     __device__ __forceinline__ void operator()(const f32x4 (&acc)[2][2][4][2], const Unit& u, int wr, int wc, int fr, int fq) const {
;         const int row0 = u.pm * BM + wr * 64 + fr, col0 = u.pn * HALF + wc * 32 + 8 * fq;
; #pragma unroll
;         for (int ai = 0; ai < 2; ++ai)
; #pragma unroll
;             for (int m = 0; m < 4; ++m) { bf16_t* rowp = O + (size_t)(row0 + ai * HALF + m * 16) * ldc + col0;
;                 const f32x4 g0 = acc[ai][0][m][0], g1 = acc[ai][0][m][1], u0 = acc[ai][1][m][0], u1 = acc[ai][1][m][1];
;                 u32x4 w; w.x = pk2(silu(g0[0]) * u0[0], silu(g0[1]) * u0[1]); w.y = pk2(silu(g0[2]) * u0[2], silu(g0[3]) * u0[3]);
;                 w.z = pk2(silu(g1[0]) * u1[0], silu(g1[1]) * u1[1]); w.w = pk2(silu(g1[2]) * u1[2], silu(g1[3]) * u1[3]);
;                 *(u32x4*)rowp = w; }
	v_mul_f32_e32 v69, v69, v71
	v_cvt_pk_bf16_f32 v79, v68, v69
	v_add_f32_e32 v70, 1.0, v70
	v_rcp_f32_e32 v70, v70
	v_add_u32_e32 v68, 0x80, v162
	v_mad_i64_i32 v[68:69], s[16:17], v68, s9, v[156:157]
	v_mul_f32_e32 v64, v64, v70
	v_mul_f32_e32 v60, v64, v60
	v_mul_f32_e32 v64, 0xbfb8aa3b, v65
	v_exp_f32_e32 v64, v64
	v_lshl_add_u64 v[68:69], v[68:69], 0, v[158:159]
	global_store_dwordx4 v[84:85], v[76:79], off
	v_add_f32_e32 v64, 1.0, v64
	v_rcp_f32_e32 v64, v64
	s_nop 0
	v_mul_f32_e32 v64, v65, v64
	v_mul_f32_e32 v61, v64, v61
	v_cvt_pk_bf16_f32 v60, v60, v61
	v_mul_f32_e32 v61, 0xbfb8aa3b, v66
	v_exp_f32_e32 v61, v61
	s_nop 0
	v_add_f32_e32 v61, 1.0, v61
	v_rcp_f32_e32 v61, v61
	s_nop 0
	v_mul_f32_e32 v61, v66, v61
	v_mul_f32_e32 v61, v61, v62
	v_mul_f32_e32 v62, 0xbfb8aa3b, v67
	v_exp_f32_e32 v62, v62
	s_nop 0
	v_add_f32_e32 v62, 1.0, v62
	v_rcp_f32_e32 v62, v62
	s_nop 0
	v_mul_f32_e32 v62, v67, v62
	v_mul_f32_e32 v62, v62, v63
	v_cvt_pk_bf16_f32 v61, v61, v62
	v_mul_f32_e32 v62, 0xbfb8aa3b, v56
	v_exp_f32_e32 v62, v62
	s_nop 0
	v_add_f32_e32 v62, 1.0, v62
	v_rcp_f32_e32 v62, v62
	s_nop 0
	v_mul_f32_e32 v56, v56, v62
	v_mul_f32_e32 v52, v56, v52
	v_mul_f32_e32 v56, 0xbfb8aa3b, v57
	v_exp_f32_e32 v56, v56
	s_nop 0
	v_add_f32_e32 v56, 1.0, v56
	v_rcp_f32_e32 v56, v56
	s_nop 0
	v_mul_f32_e32 v56, v57, v56
	v_mul_f32_e32 v53, v56, v53
	v_cvt_pk_bf16_f32 v62, v52, v53
	v_mul_f32_e32 v52, 0xbfb8aa3b, v58
	v_exp_f32_e32 v52, v52
	v_mul_f32_e32 v53, 0xbfb8aa3b, v59
	v_exp_f32_e32 v53, v53
	v_add_f32_e32 v52, 1.0, v52
	v_rcp_f32_e32 v52, v52
	v_add_f32_e32 v53, 1.0, v53
	v_rcp_f32_e32 v53, v53
	v_mul_f32_e32 v52, v58, v52
	v_mul_f32_e32 v52, v52, v54
	v_mul_f32_e32 v54, 0xbfb8aa3b, v48
	v_exp_f32_e32 v54, v54
	v_mul_f32_e32 v53, v59, v53
	v_mul_f32_e32 v53, v53, v55
	v_cvt_pk_bf16_f32 v63, v52, v53
	v_add_f32_e32 v54, 1.0, v54
	v_rcp_f32_e32 v54, v54
	v_add_u32_e32 v52, 0x90, v162
	v_mad_i64_i32 v[52:53], s[16:17], v52, s9, v[156:157]
	v_mul_f32_e32 v48, v48, v54
	v_mul_f32_e32 v44, v48, v44
	v_mul_f32_e32 v48, 0xbfb8aa3b, v49
	v_exp_f32_e32 v48, v48
	v_lshl_add_u64 v[52:53], v[52:53], 0, v[158:159]
	global_store_dwordx4 v[68:69], v[60:63], off
	v_add_f32_e32 v48, 1.0, v48
	v_rcp_f32_e32 v48, v48
	s_nop 0
	v_mul_f32_e32 v48, v49, v48
	v_mul_f32_e32 v45, v48, v45
	v_cvt_pk_bf16_f32 v44, v44, v45
	v_mul_f32_e32 v45, 0xbfb8aa3b, v50
	v_exp_f32_e32 v45, v45
	s_nop 0
	v_add_f32_e32 v45, 1.0, v45
	v_rcp_f32_e32 v45, v45
	s_nop 0
	v_mul_f32_e32 v45, v50, v45
	v_mul_f32_e32 v45, v45, v46
	v_mul_f32_e32 v46, 0xbfb8aa3b, v51
	v_exp_f32_e32 v46, v46
	s_nop 0
	v_add_f32_e32 v46, 1.0, v46
	v_rcp_f32_e32 v46, v46
	s_nop 0
	v_mul_f32_e32 v46, v51, v46
	v_mul_f32_e32 v46, v46, v47
	v_cvt_pk_bf16_f32 v45, v45, v46
	v_mul_f32_e32 v46, 0xbfb8aa3b, v40
	v_exp_f32_e32 v46, v46
	s_nop 0
	v_add_f32_e32 v46, 1.0, v46
	v_rcp_f32_e32 v46, v46
	s_nop 0
	v_mul_f32_e32 v40, v40, v46
	v_mul_f32_e32 v36, v40, v36
	v_mul_f32_e32 v40, 0xbfb8aa3b, v41
	v_exp_f32_e32 v40, v40
	s_nop 0
	v_add_f32_e32 v40, 1.0, v40
	v_rcp_f32_e32 v40, v40
	s_nop 0
	v_mul_f32_e32 v40, v41, v40
	v_mul_f32_e32 v37, v40, v37
	v_cvt_pk_bf16_f32 v46, v36, v37
	v_mul_f32_e32 v36, 0xbfb8aa3b, v42
	v_exp_f32_e32 v36, v36
	v_mul_f32_e32 v37, 0xbfb8aa3b, v43
	v_exp_f32_e32 v37, v37
	v_add_f32_e32 v36, 1.0, v36
	v_rcp_f32_e32 v36, v36
	v_add_f32_e32 v37, 1.0, v37
	v_rcp_f32_e32 v37, v37
	v_mul_f32_e32 v36, v42, v36
	v_mul_f32_e32 v36, v36, v38
	v_mul_f32_e32 v38, 0xbfb8aa3b, v32
	v_exp_f32_e32 v38, v38
	v_mul_f32_e32 v37, v43, v37
	v_mul_f32_e32 v37, v37, v39
	v_cvt_pk_bf16_f32 v47, v36, v37
	v_add_f32_e32 v38, 1.0, v38
; __device__ __forceinline__ unsigned pk2(float lo, float hi) { unsigned r; asm("v_cvt_pk_bf16_f32 %0, %1, %2" : "=v"(r) : "v"(lo), "v"(hi)); return r; }
; __device__ __forceinline__ float silu(float x) { return x * sigm(x); }
; #define PG8_WAIT_V(n) asm volatile("s_waitcnt vmcnt(" #n ")" ::: "memory")
; #define PG8_BAR __builtin_amdgcn_s_barrier()
;     __device__ __forceinline__ void operator()(const f32x4 (&acc)[2][2][4][2], const Unit& u, int wr, int wc, int fr, int fq) const {
;     ...
;             for (int m = 0; m < 4; ++m) { bf16_t* rowp = O + (size_t)(row0 + ai * HALF + m * 16) * ldc + col0;
;                 const f32x4 g0 = acc[ai][0][m][0], g1 = acc[ai][0][m][1], u0 = acc[ai][1][m][0], u1 = acc[ai][1][m][1];
;                 u32x4 w; w.x = pk2(silu(g0[0]) * u0[0], silu(g0[1]) * u0[1]); w.y = pk2(silu(g0[2]) * u0[2], silu(g0[3]) * u0[3]);
;                 w.z = pk2(silu(g1[0]) * u1[0], silu(g1[1]) * u1[1]); w.w = pk2(silu(g1[2]) * u1[2], silu(g1[3]) * u1[3]);
;                 *(u32x4*)rowp = w; }
; template <class Epi>
; __device__ __forceinline__ void gemm_phase(LAS unsigned char* lds, const Gemm g, const int G, const int cidx, const Epi& E) {
;     ...
;         if (!has_next) break;
; #pragma unroll
;         for (int a = 0; a < 2; ++a)
; #pragma unroll
;             for (int b = 0; b < 2; ++b)
; #pragma unroll
;                 for (int m = 0; m < 4; ++m)
; #pragma unroll
;                     for (int n = 0; n < 2; ++n) acc[a][b][m][n] = ZERO4;
;         cur = nxt; cA = nA; cB = nB; ++ui;
;     }
;     PG8_WAIT_V(0);
;     if (wr == 0) PG8_BAR;
;     PG8_BAR;
	v_rcp_f32_e32 v38, v38
	v_add_u32_e32 v36, 0xa0, v162
	v_mad_i64_i32 v[36:37], s[16:17], v36, s9, v[156:157]
	v_mul_f32_e32 v32, v32, v38
	v_mul_f32_e32 v28, v32, v28
	v_mul_f32_e32 v32, 0xbfb8aa3b, v33
	v_exp_f32_e32 v32, v32
	v_lshl_add_u64 v[36:37], v[36:37], 0, v[158:159]
	global_store_dwordx4 v[52:53], v[44:47], off
	v_add_f32_e32 v32, 1.0, v32
	v_rcp_f32_e32 v32, v32
	s_nop 0
	v_mul_f32_e32 v32, v33, v32
	v_mul_f32_e32 v29, v32, v29
	v_cvt_pk_bf16_f32 v28, v28, v29
	v_mul_f32_e32 v29, 0xbfb8aa3b, v34
	v_exp_f32_e32 v29, v29
	s_nop 0
	v_add_f32_e32 v29, 1.0, v29
	v_rcp_f32_e32 v29, v29
	s_nop 0
	v_mul_f32_e32 v29, v34, v29
	v_mul_f32_e32 v29, v29, v30
	v_mul_f32_e32 v30, 0xbfb8aa3b, v35
	v_exp_f32_e32 v30, v30
	s_nop 0
	v_add_f32_e32 v30, 1.0, v30
	v_rcp_f32_e32 v30, v30
	s_nop 0
	v_mul_f32_e32 v30, v35, v30
	v_mul_f32_e32 v30, v30, v31
	v_cvt_pk_bf16_f32 v29, v29, v30
	v_mul_f32_e32 v30, 0xbfb8aa3b, v24
	v_exp_f32_e32 v30, v30
	s_nop 0
	v_add_f32_e32 v30, 1.0, v30
	v_rcp_f32_e32 v30, v30
	s_nop 0
	v_mul_f32_e32 v24, v24, v30
	v_mul_f32_e32 v20, v24, v20
	v_mul_f32_e32 v24, 0xbfb8aa3b, v25
	v_exp_f32_e32 v24, v24
	s_nop 0
	v_add_f32_e32 v24, 1.0, v24
	v_rcp_f32_e32 v24, v24
	s_nop 0
	v_mul_f32_e32 v24, v25, v24
	v_mul_f32_e32 v21, v24, v21
	v_cvt_pk_bf16_f32 v30, v20, v21
	v_mul_f32_e32 v20, 0xbfb8aa3b, v26
	v_exp_f32_e32 v20, v20
	v_mul_f32_e32 v21, 0xbfb8aa3b, v27
	v_exp_f32_e32 v21, v21
	v_add_f32_e32 v20, 1.0, v20
	v_rcp_f32_e32 v20, v20
	v_add_f32_e32 v21, 1.0, v21
	v_rcp_f32_e32 v21, v21
	v_mul_f32_e32 v20, v26, v20
	v_mul_f32_e32 v20, v20, v22
	v_mul_f32_e32 v22, 0xbfb8aa3b, v16
	v_exp_f32_e32 v22, v22
	v_mul_f32_e32 v21, v27, v21
	v_mul_f32_e32 v21, v21, v23
	v_cvt_pk_bf16_f32 v31, v20, v21
	v_add_f32_e32 v22, 1.0, v22
	v_rcp_f32_e32 v22, v22
	v_add_u32_e32 v20, 0xb0, v162
	v_mad_i64_i32 v[20:21], s[16:17], v20, s9, v[156:157]
	v_mul_f32_e32 v16, v16, v22
	v_mul_f32_e32 v12, v16, v12
	v_mul_f32_e32 v16, 0xbfb8aa3b, v17
	v_exp_f32_e32 v16, v16
	v_lshl_add_u64 v[20:21], v[20:21], 0, v[158:159]
	s_mov_b32 s16, s8
	global_store_dwordx4 v[36:37], v[28:31], off
	v_add_f32_e32 v16, 1.0, v16
	v_rcp_f32_e32 v16, v16
	s_nop 0
	v_mul_f32_e32 v16, v17, v16
	v_mul_f32_e32 v13, v16, v13
	v_cvt_pk_bf16_f32 v12, v12, v13
	v_mul_f32_e32 v13, 0xbfb8aa3b, v18
	v_exp_f32_e32 v13, v13
	s_nop 0
	v_add_f32_e32 v13, 1.0, v13
	v_rcp_f32_e32 v13, v13
	s_nop 0
	v_mul_f32_e32 v13, v18, v13
	v_mul_f32_e32 v13, v13, v14
	v_mul_f32_e32 v14, 0xbfb8aa3b, v19
	v_exp_f32_e32 v14, v14
	s_nop 0
	v_add_f32_e32 v14, 1.0, v14
	v_rcp_f32_e32 v14, v14
	s_nop 0
	v_mul_f32_e32 v14, v19, v14
	v_mul_f32_e32 v14, v14, v15
	v_cvt_pk_bf16_f32 v13, v13, v14
	v_mul_f32_e32 v14, 0xbfb8aa3b, v8
	v_exp_f32_e32 v14, v14
	s_nop 0
	v_add_f32_e32 v14, 1.0, v14
	v_rcp_f32_e32 v14, v14
	s_nop 0
	v_mul_f32_e32 v8, v8, v14
	v_mul_f32_e32 v4, v8, v4
	v_mul_f32_e32 v8, 0xbfb8aa3b, v9
	v_exp_f32_e32 v8, v8
	s_nop 0
	v_add_f32_e32 v8, 1.0, v8
	v_rcp_f32_e32 v8, v8
	s_nop 0
	v_mul_f32_e32 v8, v9, v8
	v_mul_f32_e32 v5, v8, v5
	v_cvt_pk_bf16_f32 v14, v4, v5
	v_mul_f32_e32 v4, 0xbfb8aa3b, v10
	v_mul_f32_e32 v5, 0xbfb8aa3b, v11
	v_exp_f32_e32 v4, v4
	v_exp_f32_e32 v5, v5
	v_add_f32_e32 v4, 1.0, v4
	v_add_f32_e32 v5, 1.0, v5
	v_rcp_f32_e32 v4, v4
	v_rcp_f32_e32 v5, v5
	v_mul_f32_e32 v4, v10, v4
	v_mul_f32_e32 v5, v11, v5
	v_mul_f32_e32 v4, v4, v6
	v_mul_f32_e32 v5, v5, v7
	v_cvt_pk_bf16_f32 v15, v4, v5
	global_store_dwordx4 v[20:21], v[12:15], off
	s_cbranch_vccz .LBB0_79
	s_waitcnt vmcnt(0)
	s_cmpk_gt_u32 s95, 0xff
	s_mov_b32 s73, s83
	v_readlane_b32 s79, v255, 21
	s_cbranch_scc1 .LBB0_86
	s_barrier

; #define PG8_STAGE(bufoff, gbase, voff) do { _Pragma("unroll") for (int _i = 0; _i < 2; ++_i) \
;         __builtin_amdgcn_global_load_lds((const unsigned*)((const char*)(gbase) + (voff)[_i]), (LAS unsigned*)(lds + (bufoff) + ldsw + _i * 8192), 16, 0, 0); } while (0)
; #define PG8_LDA(dst, b, h) do { _Pragma("unroll") for (int m = 0; m < 4; ++m) _Pragma("unroll") for (int k = 0; k < 2; ++k) dst[m][k] = *(const LAS bf16x8*)(lds + PG8_SA(b, h) + aoff + m * 2048 + k * 1024); } while (0)
; #define PG8_LDB(dst, b, h) do { _Pragma("unroll") for (int n = 0; n < 2; ++n) _Pragma("unroll") for (int k = 0; k < 2; ++k) dst[n][k] = *(const LAS bf16x8*)(lds + PG8_SB(b, h) + boff + n * 2048 + k * 1024); } while (0)
; #define PG8_MMA(ai, bj, At, Bt) do { __builtin_amdgcn_s_setprio(1); _Pragma("unroll") for (int m = 0; m < 4; ++m) _Pragma("unroll") for (int n = 0; n < 2; ++n) _Pragma("unroll") for (int k = 0; k < 2; ++k) \
;         acc[ai][bj][m][n] = __builtin_amdgcn_mfma_f32_16x16x32_bf16(Bt[n][k], At[m][k], acc[ai][bj][m][n], 0, 0, 0); __builtin_amdgcn_s_setprio(0); } while (0)
; #define PG8_WAIT_V(n) asm volatile("s_waitcnt vmcnt(" #n ")" ::: "memory")
; #define PG8_WAIT_L(n) asm volatile("s_waitcnt lgkmcnt(" #n ")" ::: "memory")
; #define PG8_BAR __builtin_amdgcn_s_barrier()
; #define PG8_SCHED __builtin_amdgcn_sched_barrier(0)
; template <class Epi>
; __device__ __forceinline__ void gemm_phase(LAS unsigned char* lds, const Gemm g, const int G, const int cidx, const Epi& E) {
;     ...
;             const char* a1 = cA + (size_t)(t + 1) * kstep;
;             const char* a2 = last ? nA : cA + (size_t)(t + 2) * kstep; const char* b2 = last ? nB : cB + (size_t)(t + 2) * kstep;
;             const char* a3 = a2 + kstep; const char* b3 = b2 + kstep;
;             PG8_LDB(B0, 0, 0); PG8_LDB(B1, 0, 1); PG8_SCHED; PG8_LDA(At, 0, 0); PG8_STAGE(PG8_SA(1, 1), a1 + hstep, voffA);
;             PG8_WAIT_V(8); PG8_WAIT_L(0); PG8_BAR; PG8_MMA(0, 0, At, B0); PG8_MMA(0, 1, At, B1); PG8_BAR; PG8_SCHED;
;             PG8_LDA(At, 0, 1); PG8_STAGE(PG8_SB(0, 0), b2, voffB); PG8_STAGE(PG8_SB(0, 1), b2 + hstep, voffB); PG8_STAGE(PG8_SA(0, 0), a2, voffA);
;             PG8_WAIT_V(8); PG8_WAIT_L(0); PG8_BAR; PG8_MMA(1, 0, At, B0); PG8_MMA(1, 1, At, B1); PG8_BAR; PG8_SCHED;
.LBB0_216:
	s_add_u32 s72, s8, s70
	s_addc_u32 s73, s9, s71
	s_add_u32 s72, s72, 0x100
	s_addc_u32 s73, s73, 0
	s_add_u32 s83, s43, s70
	s_addc_u32 s86, s44, s71
	s_add_i32 s87, 0, 0x10000
	s_cmpk_eq_i32 s70, 0x700
	s_cselect_b32 s75, s31, s73
	s_cselect_b32 s74, s45, s72
	v_add_u32_e32 v3, s87, v158
	s_cselect_b32 s73, s29, s86
	s_cselect_b32 s72, s68, s83
	s_add_i32 s83, 0, 0x14000
	ds_read_b128 v[132:135], v3
	ds_read_b128 v[140:143], v3 offset:1024
	ds_read_b128 v[160:163], v3 offset:2048
	ds_read_b128 v[164:167], v3 offset:3072
	v_add_u32_e32 v3, s83, v158
	ds_read_b128 v[168:171], v3
	ds_read_b128 v[172:175], v3 offset:1024
	ds_read_b128 v[176:179], v3 offset:2048
	ds_read_b128 v[180:183], v3 offset:3072
	v_lshl_add_u64 v[200:201], v[154:155], 0, s[70:71]
	s_add_i32 m0, s19, 0xc000
	ds_read_b128 v[184:187], v159
	ds_read_b128 v[188:191], v159 offset:1024
	ds_read_b128 v[192:195], v159 offset:2048
	ds_read_b128 v[196:199], v159 offset:3072
	ds_read_b128 v[214:217], v159 offset:4096
	ds_read_b128 v[218:221], v159 offset:5120
	ds_read_b128 v[222:225], v159 offset:6144
	ds_read_b128 v[226:229], v159 offset:7168
	global_load_lds_dwordx4 v[200:201], off
	v_lshl_add_u64 v[200:201], v[0:1], 0, s[70:71]
	s_add_i32 m0, s19, 0xe000
	s_nop 0
	global_load_lds_dwordx4 v[200:201], off
	s_waitcnt vmcnt(8)
	s_waitcnt lgkmcnt(0)
	s_barrier
	s_setprio 1
	s_waitcnt lgkmcnt(0)
	v_mfma_f32_16x16x32_bf16 v[64:67], v[132:135], v[184:187], v[64:67]
	v_mfma_f32_16x16x32_bf16 v[72:75], v[160:163], v[184:187], v[72:75]
	v_mfma_f32_16x16x32_bf16 v[92:95], v[132:135], v[192:195], v[92:95]
	v_mfma_f32_16x16x32_bf16 v[96:99], v[160:163], v[192:195], v[96:99]
	v_mfma_f32_16x16x32_bf16 v[116:119], v[132:135], v[214:217], v[116:119]
	v_mfma_f32_16x16x32_bf16 v[124:127], v[160:163], v[214:217], v[124:127]
	v_mfma_f32_16x16x32_bf16 v[112:115], v[132:135], v[222:225], v[112:115]
	v_mfma_f32_16x16x32_bf16 v[100:103], v[160:163], v[222:225], v[100:103]
	v_mfma_f32_16x16x32_bf16 v[64:67], v[140:143], v[188:191], v[64:67]
	v_mfma_f32_16x16x32_bf16 v[72:75], v[164:167], v[188:191], v[72:75]
	v_mfma_f32_16x16x32_bf16 v[92:95], v[140:143], v[196:199], v[92:95]
	v_mfma_f32_16x16x32_bf16 v[96:99], v[164:167], v[196:199], v[96:99]
	v_mfma_f32_16x16x32_bf16 v[116:119], v[140:143], v[218:221], v[116:119]
	v_mfma_f32_16x16x32_bf16 v[124:127], v[164:167], v[218:221], v[124:127]
	v_mfma_f32_16x16x32_bf16 v[112:115], v[140:143], v[226:229], v[112:115]
	v_mfma_f32_16x16x32_bf16 v[100:103], v[164:167], v[226:229], v[100:103]
	s_setprio 0
	s_setprio 1
	v_mfma_f32_16x16x32_bf16 v[76:79], v[168:171], v[184:187], v[76:79]
	v_mfma_f32_16x16x32_bf16 v[84:87], v[176:179], v[184:187], v[84:87]
	v_mfma_f32_16x16x32_bf16 v[104:107], v[168:171], v[192:195], v[104:107]
	v_mfma_f32_16x16x32_bf16 v[108:111], v[176:179], v[192:195], v[108:111]
	v_mfma_f32_16x16x32_bf16 v[128:131], v[168:171], v[214:217], v[128:131]
	v_mfma_f32_16x16x32_bf16 v[120:123], v[176:179], v[214:217], v[120:123]
	v_mfma_f32_16x16x32_bf16 v[88:91], v[168:171], v[222:225], v[88:91]
	v_mfma_f32_16x16x32_bf16 v[80:83], v[176:179], v[222:225], v[80:83]
	v_mfma_f32_16x16x32_bf16 v[76:79], v[172:175], v[188:191], v[76:79]
	v_mfma_f32_16x16x32_bf16 v[84:87], v[180:183], v[188:191], v[84:87]
	v_mfma_f32_16x16x32_bf16 v[104:107], v[172:175], v[196:199], v[104:107]
	v_mfma_f32_16x16x32_bf16 v[108:111], v[180:183], v[196:199], v[108:111]
	v_mfma_f32_16x16x32_bf16 v[128:131], v[172:175], v[218:221], v[128:131]
	v_mfma_f32_16x16x32_bf16 v[120:123], v[180:183], v[218:221], v[120:123]
	v_mfma_f32_16x16x32_bf16 v[88:91], v[172:175], v[226:229], v[88:91]
	v_mfma_f32_16x16x32_bf16 v[80:83], v[180:183], v[226:229], v[80:83]
	s_setprio 0
	s_barrier
	s_sleep 2
	s_add_i32 s86, s87, s40
	v_lshl_add_u64 v[200:201], s[72:73], 0, v[146:147]
	s_mov_b32 m0, s86
	ds_read_b128 v[184:187], v159 offset:16384
	ds_read_b128 v[188:191], v159 offset:17408
	ds_read_b128 v[192:195], v159 offset:18432
	ds_read_b128 v[196:199], v159 offset:19456
	ds_read_b128 v[214:217], v159 offset:20480
	ds_read_b128 v[218:221], v159 offset:21504
	ds_read_b128 v[222:225], v159 offset:22528
	ds_read_b128 v[226:229], v159 offset:23552
	global_load_lds_dwordx4 v[200:201], off
	s_add_i32 m0, s86, 0x2000
	s_add_u32 s86, s72, 0x40000
	v_lshl_add_u64 v[230:231], s[72:73], 0, v[148:149]
	s_addc_u32 s87, s73, 0
	s_add_i32 s83, s83, s40
	global_load_lds_dwordx4 v[230:231], off
	v_lshl_add_u64 v[232:233], s[86:87], 0, v[146:147]
	s_mov_b32 m0, s83
	v_lshl_add_u64 v[234:235], s[74:75], 0, v[148:149]
	global_load_lds_dwordx4 v[232:233], off
	v_lshl_add_u64 v[232:233], s[86:87], 0, v[148:149]
	s_add_i32 m0, s83, 0x2000
	s_nop 0
	global_load_lds_dwordx4 v[232:233], off
	v_lshl_add_u64 v[232:233], s[74:75], 0, v[146:147]
	s_mov_b32 m0, s19
	s_nop 0
	global_load_lds_dwordx4 v[232:233], off
	s_mov_b32 m0, s76
	s_nop 0
	global_load_lds_dwordx4 v[234:235], off
	s_waitcnt vmcnt(8)
	s_waitcnt lgkmcnt(0)
	s_barrier
; #define PG8_STAGE(bufoff, gbase, voff) do { _Pragma("unroll") for (int _i = 0; _i < 2; ++_i) \
;         __builtin_amdgcn_global_load_lds((const unsigned*)((const char*)(gbase) + (voff)[_i]), (LAS unsigned*)(lds + (bufoff) + ldsw + _i * 8192), 16, 0, 0); } while (0)
; #define PG8_LDA(dst, b, h) do { _Pragma("unroll") for (int m = 0; m < 4; ++m) _Pragma("unroll") for (int k = 0; k < 2; ++k) dst[m][k] = *(const LAS bf16x8*)(lds + PG8_SA(b, h) + aoff + m * 2048 + k * 1024); } while (0)
; #define PG8_LDB(dst, b, h) do { _Pragma("unroll") for (int n = 0; n < 2; ++n) _Pragma("unroll") for (int k = 0; k < 2; ++k) dst[n][k] = *(const LAS bf16x8*)(lds + PG8_SB(b, h) + boff + n * 2048 + k * 1024); } while (0)
; #define PG8_MMA(ai, bj, At, Bt) do { __builtin_amdgcn_s_setprio(1); _Pragma("unroll") for (int m = 0; m < 4; ++m) _Pragma("unroll") for (int n = 0; n < 2; ++n) _Pragma("unroll") for (int k = 0; k < 2; ++k) \
;         acc[ai][bj][m][n] = __builtin_amdgcn_mfma_f32_16x16x32_bf16(Bt[n][k], At[m][k], acc[ai][bj][m][n], 0, 0, 0); __builtin_amdgcn_s_setprio(0); } while (0)
; #define PG8_WAIT_V(n) asm volatile("s_waitcnt vmcnt(" #n ")" ::: "memory")
; #define PG8_WAIT_L(n) asm volatile("s_waitcnt lgkmcnt(" #n ")" ::: "memory")
; #define PG8_BAR __builtin_amdgcn_s_barrier()
; #define PG8_SCHED __builtin_amdgcn_sched_barrier(0)
; template <class Epi>
; __device__ __forceinline__ void gemm_phase(LAS unsigned char* lds, const Gemm g, const int G, const int cidx, const Epi& E) {
;     ...
;             PG8_WAIT_V(8); PG8_WAIT_L(0); PG8_BAR; PG8_MMA(1, 0, At, B0); PG8_MMA(1, 1, At, B1); PG8_BAR; PG8_SCHED;
;             PG8_LDB(B0, 1, 0); PG8_LDB(B1, 1, 1); PG8_SCHED; PG8_LDA(At, 1, 0); PG8_STAGE(PG8_SA(0, 1), a2 + hstep, voffA);
;             PG8_WAIT_V(8); PG8_WAIT_L(0); PG8_BAR; PG8_MMA(0, 0, At, B0); PG8_MMA(0, 1, At, B1); PG8_BAR; PG8_SCHED;
	s_setprio 1
	s_waitcnt lgkmcnt(0)
	v_mfma_f32_16x16x32_bf16 v[68:71], v[132:135], v[184:187], v[68:71]
	v_mfma_f32_16x16x32_bf16 v[60:63], v[160:163], v[184:187], v[60:63]
	v_mfma_f32_16x16x32_bf16 v[48:51], v[132:135], v[192:195], v[48:51]
	v_mfma_f32_16x16x32_bf16 v[44:47], v[160:163], v[192:195], v[44:47]
	v_mfma_f32_16x16x32_bf16 v[32:35], v[132:135], v[214:217], v[32:35]
	v_mfma_f32_16x16x32_bf16 v[28:31], v[160:163], v[214:217], v[28:31]
	v_mfma_f32_16x16x32_bf16 v[16:19], v[132:135], v[222:225], v[16:19]
	v_mfma_f32_16x16x32_bf16 v[12:15], v[160:163], v[222:225], v[12:15]
	v_mfma_f32_16x16x32_bf16 v[68:71], v[140:143], v[188:191], v[68:71]
	v_mfma_f32_16x16x32_bf16 v[60:63], v[164:167], v[188:191], v[60:63]
	v_mfma_f32_16x16x32_bf16 v[48:51], v[140:143], v[196:199], v[48:51]
	v_mfma_f32_16x16x32_bf16 v[44:47], v[164:167], v[196:199], v[44:47]
	v_mfma_f32_16x16x32_bf16 v[32:35], v[140:143], v[218:221], v[32:35]
	v_mfma_f32_16x16x32_bf16 v[28:31], v[164:167], v[218:221], v[28:31]
	v_mfma_f32_16x16x32_bf16 v[16:19], v[140:143], v[226:229], v[16:19]
	v_mfma_f32_16x16x32_bf16 v[12:15], v[164:167], v[226:229], v[12:15]
	s_setprio 0
	s_setprio 1
	v_mfma_f32_16x16x32_bf16 v[56:59], v[168:171], v[184:187], v[56:59]
	v_mfma_f32_16x16x32_bf16 v[52:55], v[176:179], v[184:187], v[52:55]
	v_mfma_f32_16x16x32_bf16 v[40:43], v[168:171], v[192:195], v[40:43]
	v_mfma_f32_16x16x32_bf16 v[36:39], v[176:179], v[192:195], v[36:39]
	v_mfma_f32_16x16x32_bf16 v[24:27], v[168:171], v[214:217], v[24:27]
	v_mfma_f32_16x16x32_bf16 v[20:23], v[176:179], v[214:217], v[20:23]
	v_mfma_f32_16x16x32_bf16 v[8:11], v[168:171], v[222:225], v[8:11]
	v_mfma_f32_16x16x32_bf16 v[4:7], v[176:179], v[222:225], v[4:7]
	v_mfma_f32_16x16x32_bf16 v[56:59], v[172:175], v[188:191], v[56:59]
	v_mfma_f32_16x16x32_bf16 v[52:55], v[180:183], v[188:191], v[52:55]
	v_mfma_f32_16x16x32_bf16 v[40:43], v[172:175], v[196:199], v[40:43]
	v_mfma_f32_16x16x32_bf16 v[36:39], v[180:183], v[196:199], v[36:39]
	v_mfma_f32_16x16x32_bf16 v[24:27], v[172:175], v[218:221], v[24:27]
	v_mfma_f32_16x16x32_bf16 v[20:23], v[180:183], v[218:221], v[20:23]
	v_mfma_f32_16x16x32_bf16 v[8:11], v[172:175], v[226:229], v[8:11]
	v_mfma_f32_16x16x32_bf16 v[4:7], v[180:183], v[226:229], v[4:7]
	s_setprio 0
	s_barrier
	s_sleep 2
	s_add_i32 s83, 0, 0x18000
	v_add_u32_e32 v3, s83, v158
	s_add_i32 s86, 0, 0x1c000
	ds_read_b128 v[132:135], v3
	ds_read_b128 v[140:143], v3 offset:1024
	ds_read_b128 v[160:163], v3 offset:2048
	ds_read_b128 v[164:167], v3 offset:3072
	v_add_u32_e32 v3, s86, v158
	ds_read_b128 v[168:171], v3
	ds_read_b128 v[172:175], v3 offset:1024
	ds_read_b128 v[176:179], v3 offset:2048
	ds_read_b128 v[180:183], v3 offset:3072
	s_add_u32 s74, s74, 0x40000
	s_addc_u32 s75, s75, 0
	s_mov_b32 m0, s84
	v_lshl_add_u64 v[236:237], s[74:75], 0, v[146:147]
	ds_read_b128 v[184:187], v159 offset:32768
	ds_read_b128 v[188:191], v159 offset:33792
	ds_read_b128 v[192:195], v159 offset:34816
	ds_read_b128 v[196:199], v159 offset:35840
	ds_read_b128 v[214:217], v159 offset:36864
	ds_read_b128 v[218:221], v159 offset:37888
	ds_read_b128 v[222:225], v159 offset:38912
	ds_read_b128 v[226:229], v159 offset:39936
	global_load_lds_dwordx4 v[236:237], off
	v_lshl_add_u64 v[236:237], s[74:75], 0, v[148:149]
	s_mov_b32 m0, s97
	s_nop 0
	global_load_lds_dwordx4 v[236:237], off
	s_waitcnt vmcnt(8)
	s_waitcnt lgkmcnt(0)
	s_barrier
	s_setprio 1
	s_waitcnt lgkmcnt(0)
	v_mfma_f32_16x16x32_bf16 v[64:67], v[132:135], v[184:187], v[64:67]
	v_mfma_f32_16x16x32_bf16 v[72:75], v[160:163], v[184:187], v[72:75]
	v_mfma_f32_16x16x32_bf16 v[92:95], v[132:135], v[192:195], v[92:95]
	v_mfma_f32_16x16x32_bf16 v[96:99], v[160:163], v[192:195], v[96:99]
	v_mfma_f32_16x16x32_bf16 v[116:119], v[132:135], v[214:217], v[116:119]
	v_mfma_f32_16x16x32_bf16 v[124:127], v[160:163], v[214:217], v[124:127]
	v_mfma_f32_16x16x32_bf16 v[112:115], v[132:135], v[222:225], v[112:115]
	v_mfma_f32_16x16x32_bf16 v[100:103], v[160:163], v[222:225], v[100:103]
	v_mfma_f32_16x16x32_bf16 v[64:67], v[140:143], v[188:191], v[64:67]
	v_mfma_f32_16x16x32_bf16 v[72:75], v[164:167], v[188:191], v[72:75]
	v_mfma_f32_16x16x32_bf16 v[92:95], v[140:143], v[196:199], v[92:95]
	v_mfma_f32_16x16x32_bf16 v[96:99], v[164:167], v[196:199], v[96:99]
	v_mfma_f32_16x16x32_bf16 v[116:119], v[140:143], v[218:221], v[116:119]
	v_mfma_f32_16x16x32_bf16 v[124:127], v[164:167], v[218:221], v[124:127]
	v_mfma_f32_16x16x32_bf16 v[112:115], v[140:143], v[226:229], v[112:115]
	v_mfma_f32_16x16x32_bf16 v[100:103], v[164:167], v[226:229], v[100:103]
	s_setprio 0
	s_setprio 1
	v_mfma_f32_16x16x32_bf16 v[76:79], v[168:171], v[184:187], v[76:79]
	v_mfma_f32_16x16x32_bf16 v[84:87], v[176:179], v[184:187], v[84:87]
	v_mfma_f32_16x16x32_bf16 v[104:107], v[168:171], v[192:195], v[104:107]
	v_mfma_f32_16x16x32_bf16 v[108:111], v[176:179], v[192:195], v[108:111]
	v_mfma_f32_16x16x32_bf16 v[128:131], v[168:171], v[214:217], v[128:131]
	v_mfma_f32_16x16x32_bf16 v[120:123], v[176:179], v[214:217], v[120:123]
	v_mfma_f32_16x16x32_bf16 v[88:91], v[168:171], v[222:225], v[88:91]
	v_mfma_f32_16x16x32_bf16 v[80:83], v[176:179], v[222:225], v[80:83]
	v_mfma_f32_16x16x32_bf16 v[76:79], v[172:175], v[188:191], v[76:79]
	v_mfma_f32_16x16x32_bf16 v[84:87], v[180:183], v[188:191], v[84:87]
	v_mfma_f32_16x16x32_bf16 v[104:107], v[172:175], v[196:199], v[104:107]
	v_mfma_f32_16x16x32_bf16 v[108:111], v[180:183], v[196:199], v[108:111]
	v_mfma_f32_16x16x32_bf16 v[128:131], v[172:175], v[218:221], v[128:131]
	v_mfma_f32_16x16x32_bf16 v[120:123], v[180:183], v[218:221], v[120:123]
	v_mfma_f32_16x16x32_bf16 v[88:91], v[172:175], v[226:229], v[88:91]
	v_mfma_f32_16x16x32_bf16 v[80:83], v[180:183], v[226:229], v[80:83]
	s_setprio 0
	s_barrier
; #define PG8_STAGE(bufoff, gbase, voff) do { _Pragma("unroll") for (int _i = 0; _i < 2; ++_i) \
;         __builtin_amdgcn_global_load_lds((const unsigned*)((const char*)(gbase) + (voff)[_i]), (LAS unsigned*)(lds + (bufoff) + ldsw + _i * 8192), 16, 0, 0); } while (0)
; #define PG8_LDA(dst, b, h) do { _Pragma("unroll") for (int m = 0; m < 4; ++m) _Pragma("unroll") for (int k = 0; k < 2; ++k) dst[m][k] = *(const LAS bf16x8*)(lds + PG8_SA(b, h) + aoff + m * 2048 + k * 1024); } while (0)
; #define PG8_MMA(ai, bj, At, Bt) do { __builtin_amdgcn_s_setprio(1); _Pragma("unroll") for (int m = 0; m < 4; ++m) _Pragma("unroll") for (int n = 0; n < 2; ++n) _Pragma("unroll") for (int k = 0; k < 2; ++k) \
;         acc[ai][bj][m][n] = __builtin_amdgcn_mfma_f32_16x16x32_bf16(Bt[n][k], At[m][k], acc[ai][bj][m][n], 0, 0, 0); __builtin_amdgcn_s_setprio(0); } while (0)
; #define PG8_WAIT_V(n) asm volatile("s_waitcnt vmcnt(" #n ")" ::: "memory")
; #define PG8_WAIT_L(n) asm volatile("s_waitcnt lgkmcnt(" #n ")" ::: "memory")
; #define PG8_BAR __builtin_amdgcn_s_barrier()
; #define PG8_SCHED __builtin_amdgcn_sched_barrier(0)
; template <class Epi>
; __device__ __forceinline__ void gemm_phase(LAS unsigned char* lds, const Gemm g, const int G, const int cidx, const Epi& E) {
;     ...
;             PG8_LDA(At, 1, 1); PG8_STAGE(PG8_SB(1, 0), b3, voffB); PG8_STAGE(PG8_SB(1, 1), b3 + hstep, voffB); PG8_STAGE(PG8_SA(1, 0), a3, voffA);
;             PG8_WAIT_V(8); PG8_WAIT_L(0); PG8_BAR; PG8_MMA(1, 0, At, B0); PG8_MMA(1, 1, At, B1); PG8_BAR; PG8_SCHED;
;         }
;         if constexpr (!Epi::AFTER_DRAIN) E(acc, cur, wr, wc, fr, fq);
;         if (!has_next) break;
; #pragma unroll
;         for (int a = 0; a < 2; ++a)
; #pragma unroll
;             for (int b = 0; b < 2; ++b)
; #pragma unroll
;                 for (int m = 0; m < 4; ++m)
; #pragma unroll
;                     for (int n = 0; n < 2; ++n) acc[a][b][m][n] = ZERO4;
;         cur = nxt; cA = nA; cB = nB; ++ui;
	s_sleep 2
	s_add_i32 s74, s83, s40
	v_lshl_add_u64 v[200:201], v[200:201], 0, s[46:47]
	s_mov_b32 m0, s74
	ds_read_b128 v[184:187], v159 offset:49152
	ds_read_b128 v[188:191], v159 offset:50176
	ds_read_b128 v[192:195], v159 offset:51200
	ds_read_b128 v[196:199], v159 offset:52224
	ds_read_b128 v[214:217], v159 offset:53248
	ds_read_b128 v[218:221], v159 offset:54272
	ds_read_b128 v[222:225], v159 offset:55296
	ds_read_b128 v[226:229], v159 offset:56320
	global_load_lds_dwordx4 v[200:201], off
	s_add_i32 m0, s74, 0x2000
	s_add_u32 s72, s72, 0x40080
	v_lshl_add_u64 v[200:201], v[230:231], 0, s[46:47]
	s_addc_u32 s73, s73, 0
	s_add_i32 s74, s86, s40
	global_load_lds_dwordx4 v[200:201], off
	v_lshl_add_u64 v[200:201], s[72:73], 0, v[146:147]
	s_mov_b32 m0, s74
	s_nop 0
	global_load_lds_dwordx4 v[200:201], off
	v_lshl_add_u64 v[200:201], s[72:73], 0, v[148:149]
	s_add_i32 m0, s74, 0x2000
	s_nop 0
	global_load_lds_dwordx4 v[200:201], off
	v_lshl_add_u64 v[200:201], v[232:233], 0, s[46:47]
	s_mov_b32 m0, s0
	s_nop 0
	global_load_lds_dwordx4 v[200:201], off
	v_lshl_add_u64 v[200:201], v[234:235], 0, s[46:47]
	s_mov_b32 m0, s2
	s_nop 0
	global_load_lds_dwordx4 v[200:201], off
	s_waitcnt vmcnt(8)
	s_waitcnt lgkmcnt(0)
	s_barrier
	s_setprio 1
	s_waitcnt lgkmcnt(0)
	v_mfma_f32_16x16x32_bf16 v[68:71], v[132:135], v[184:187], v[68:71]
	v_mfma_f32_16x16x32_bf16 v[60:63], v[160:163], v[184:187], v[60:63]
	v_mfma_f32_16x16x32_bf16 v[48:51], v[132:135], v[192:195], v[48:51]
	v_mfma_f32_16x16x32_bf16 v[44:47], v[160:163], v[192:195], v[44:47]
	v_mfma_f32_16x16x32_bf16 v[32:35], v[132:135], v[214:217], v[32:35]
	v_mfma_f32_16x16x32_bf16 v[28:31], v[160:163], v[214:217], v[28:31]
	v_mfma_f32_16x16x32_bf16 v[16:19], v[132:135], v[222:225], v[16:19]
	v_mfma_f32_16x16x32_bf16 v[12:15], v[160:163], v[222:225], v[12:15]
	v_mfma_f32_16x16x32_bf16 v[68:71], v[140:143], v[188:191], v[68:71]
	v_mfma_f32_16x16x32_bf16 v[60:63], v[164:167], v[188:191], v[60:63]
	v_mfma_f32_16x16x32_bf16 v[48:51], v[140:143], v[196:199], v[48:51]
	v_mfma_f32_16x16x32_bf16 v[44:47], v[164:167], v[196:199], v[44:47]
	v_mfma_f32_16x16x32_bf16 v[32:35], v[140:143], v[218:221], v[32:35]
	v_mfma_f32_16x16x32_bf16 v[28:31], v[164:167], v[218:221], v[28:31]
	v_mfma_f32_16x16x32_bf16 v[16:19], v[140:143], v[226:229], v[16:19]
	v_mfma_f32_16x16x32_bf16 v[12:15], v[164:167], v[226:229], v[12:15]
	s_setprio 0
	s_setprio 1
	v_mfma_f32_16x16x32_bf16 v[56:59], v[168:171], v[184:187], v[56:59]
	v_mfma_f32_16x16x32_bf16 v[52:55], v[176:179], v[184:187], v[52:55]
	v_mfma_f32_16x16x32_bf16 v[40:43], v[168:171], v[192:195], v[40:43]
	v_mfma_f32_16x16x32_bf16 v[36:39], v[176:179], v[192:195], v[36:39]
	v_mfma_f32_16x16x32_bf16 v[24:27], v[168:171], v[214:217], v[24:27]
	v_mfma_f32_16x16x32_bf16 v[20:23], v[176:179], v[214:217], v[20:23]
	v_mfma_f32_16x16x32_bf16 v[8:11], v[168:171], v[222:225], v[8:11]
	v_mfma_f32_16x16x32_bf16 v[4:7], v[176:179], v[222:225], v[4:7]
	v_mfma_f32_16x16x32_bf16 v[56:59], v[172:175], v[188:191], v[56:59]
	v_mfma_f32_16x16x32_bf16 v[52:55], v[180:183], v[188:191], v[52:55]
	v_mfma_f32_16x16x32_bf16 v[40:43], v[172:175], v[196:199], v[40:43]
	v_mfma_f32_16x16x32_bf16 v[36:39], v[180:183], v[196:199], v[36:39]
	v_mfma_f32_16x16x32_bf16 v[24:27], v[172:175], v[218:221], v[24:27]
	v_mfma_f32_16x16x32_bf16 v[20:23], v[180:183], v[218:221], v[20:23]
	v_mfma_f32_16x16x32_bf16 v[8:11], v[172:175], v[226:229], v[8:11]
	v_mfma_f32_16x16x32_bf16 v[4:7], v[180:183], v[226:229], v[4:7]
	s_setprio 0
	s_barrier
	s_sleep 2
	s_add_i32 s77, s77, 2
	s_add_u32 s70, s70, 0x100
	s_addc_u32 s71, s71, 0
	s_cmp_gt_u32 s77, 13
	s_cbranch_scc0 .LBB0_216
	s_add_u32 s70, s43, 0xffffff00
	s_addc_u32 s71, s44, -1
	s_andn2_b64 vcc, exec, s[6:7]
	s_cbranch_vccnz .LBB0_219
	v_mov_b32_e32 v4, 0
	s_mov_b32 s20, s28
	s_mov_b32 s18, s30
	s_mov_b64 s[8:9], s[36:37]
	s_mov_b32 s38, s33
	v_mov_b32_e32 v5, v4
	v_mov_b32_e32 v6, v4
	v_mov_b32_e32 v7, v4
	v_mov_b32_e32 v8, v4
	v_mov_b32_e32 v9, v4
	v_mov_b32_e32 v10, v4
	v_mov_b32_e32 v11, v4
	v_mov_b32_e32 v20, v4
	v_mov_b32_e32 v21, v4
	v_mov_b32_e32 v22, v4
	v_mov_b32_e32 v23, v4
	v_mov_b32_e32 v24, v4
	v_mov_b32_e32 v25, v4
	v_mov_b32_e32 v26, v4
	v_mov_b32_e32 v27, v4
	v_mov_b32_e32 v36, v4
	v_mov_b32_e32 v37, v4
	v_mov_b32_e32 v38, v4
	v_mov_b32_e32 v39, v4
	v_mov_b32_e32 v40, v4
	v_mov_b32_e32 v41, v4
	v_mov_b32_e32 v42, v4
	v_mov_b32_e32 v43, v4
	v_mov_b32_e32 v52, v4
	v_mov_b32_e32 v53, v4
	v_mov_b32_e32 v54, v4
	v_mov_b32_e32 v55, v4
	v_mov_b32_e32 v56, v4
	v_mov_b32_e32 v57, v4
	v_mov_b32_e32 v58, v4
	v_mov_b32_e32 v59, v4
	v_mov_b32_e32 v12, v4
	v_mov_b32_e32 v13, v4
	v_mov_b32_e32 v14, v4
	v_mov_b32_e32 v15, v4
	v_mov_b32_e32 v16, v4
	v_mov_b32_e32 v17, v4
	v_mov_b32_e32 v18, v4
	v_mov_b32_e32 v19, v4
	v_mov_b32_e32 v28, v4
	v_mov_b32_e32 v29, v4
	v_mov_b32_e32 v30, v4
	v_mov_b32_e32 v31, v4
	v_mov_b32_e32 v32, v4
	v_mov_b32_e32 v33, v4
	v_mov_b32_e32 v34, v4
	v_mov_b32_e32 v35, v4
	v_mov_b32_e32 v44, v4
	v_mov_b32_e32 v45, v4
	v_mov_b32_e32 v46, v4
	v_mov_b32_e32 v47, v4
	v_mov_b32_e32 v48, v4
	v_mov_b32_e32 v49, v4
	v_mov_b32_e32 v50, v4
	v_mov_b32_e32 v51, v4
	v_mov_b32_e32 v60, v4
	v_mov_b32_e32 v61, v4
	v_mov_b32_e32 v62, v4
	v_mov_b32_e32 v63, v4
	v_mov_b32_e32 v68, v4
	v_mov_b32_e32 v69, v4
	v_mov_b32_e32 v70, v4
	v_mov_b32_e32 v71, v4
	v_mov_b32_e32 v80, v4
	v_mov_b32_e32 v81, v4
	v_mov_b32_e32 v82, v4
	v_mov_b32_e32 v83, v4
	v_mov_b32_e32 v88, v4
	v_mov_b32_e32 v89, v4
	v_mov_b32_e32 v90, v4
	v_mov_b32_e32 v91, v4
	v_mov_b32_e32 v120, v4
	v_mov_b32_e32 v121, v4
	v_mov_b32_e32 v122, v4
	v_mov_b32_e32 v123, v4
	v_mov_b32_e32 v128, v4
	v_mov_b32_e32 v129, v4
	v_mov_b32_e32 v130, v4
	v_mov_b32_e32 v131, v4
	v_mov_b32_e32 v108, v4
	v_mov_b32_e32 v109, v4
	v_mov_b32_e32 v110, v4
	v_mov_b32_e32 v111, v4
	v_mov_b32_e32 v104, v4
	v_mov_b32_e32 v105, v4
	v_mov_b32_e32 v106, v4
	v_mov_b32_e32 v107, v4
	v_mov_b32_e32 v84, v4
	v_mov_b32_e32 v85, v4
	v_mov_b32_e32 v86, v4
	v_mov_b32_e32 v87, v4
	v_mov_b32_e32 v76, v4
	v_mov_b32_e32 v77, v4
	v_mov_b32_e32 v78, v4
	v_mov_b32_e32 v79, v4
	v_mov_b32_e32 v100, v4
	v_mov_b32_e32 v101, v4
	v_mov_b32_e32 v102, v4
	v_mov_b32_e32 v103, v4
	v_mov_b32_e32 v112, v4
	v_mov_b32_e32 v113, v4
	v_mov_b32_e32 v114, v4
	v_mov_b32_e32 v115, v4
	v_mov_b32_e32 v124, v4
	v_mov_b32_e32 v125, v4
	v_mov_b32_e32 v126, v4
	v_mov_b32_e32 v127, v4
	v_mov_b32_e32 v116, v4
	v_mov_b32_e32 v117, v4
	v_mov_b32_e32 v118, v4
	v_mov_b32_e32 v119, v4
	v_mov_b32_e32 v96, v4
	v_mov_b32_e32 v97, v4
	v_mov_b32_e32 v98, v4
	v_mov_b32_e32 v99, v4
	v_mov_b32_e32 v92, v4
	v_mov_b32_e32 v93, v4
	v_mov_b32_e32 v94, v4
	v_mov_b32_e32 v95, v4
	v_mov_b32_e32 v72, v4
	v_mov_b32_e32 v73, v4
	v_mov_b32_e32 v74, v4
	v_mov_b32_e32 v75, v4
	v_mov_b32_e32 v64, v4
	v_mov_b32_e32 v65, v4
	v_mov_b32_e32 v66, v4
	v_mov_b32_e32 v67, v4
	s_mov_b32 s83, 0x18000
	s_mov_b32 s86, 0x3fb8aa3b
	s_andn2_b64 vcc, exec, s[4:5]
	s_cbranch_vccnz .LBB0_220
	s_branch .LBB0_221

; #define PG8_STAGE(bufoff, gbase, voff) do { _Pragma("unroll") for (int _i = 0; _i < 2; ++_i) \
;         __builtin_amdgcn_global_load_lds((const unsigned*)((const char*)(gbase) + (voff)[_i]), (LAS unsigned*)(lds + (bufoff) + ldsw + _i * 8192), 16, 0, 0); } while (0)
; #define PG8_LDA(dst, b, h) do { _Pragma("unroll") for (int m = 0; m < 4; ++m) _Pragma("unroll") for (int k = 0; k < 2; ++k) dst[m][k] = *(const LAS bf16x8*)(lds + PG8_SA(b, h) + aoff + m * 2048 + k * 1024); } while (0)
; #define PG8_LDB(dst, b, h) do { _Pragma("unroll") for (int n = 0; n < 2; ++n) _Pragma("unroll") for (int k = 0; k < 2; ++k) dst[n][k] = *(const LAS bf16x8*)(lds + PG8_SB(b, h) + boff + n * 2048 + k * 1024); } while (0)
; #define PG8_MMA(ai, bj, At, Bt) do { __builtin_amdgcn_s_setprio(1); _Pragma("unroll") for (int m = 0; m < 4; ++m) _Pragma("unroll") for (int n = 0; n < 2; ++n) _Pragma("unroll") for (int k = 0; k < 2; ++k) \
;         acc[ai][bj][m][n] = __builtin_amdgcn_mfma_f32_16x16x32_bf16(Bt[n][k], At[m][k], acc[ai][bj][m][n], 0, 0, 0); __builtin_amdgcn_s_setprio(0); } while (0)
; #define PG8_WAIT_V(n) asm volatile("s_waitcnt vmcnt(" #n ")" ::: "memory")
; #define PG8_WAIT_L(n) asm volatile("s_waitcnt lgkmcnt(" #n ")" ::: "memory")
; #define PG8_BAR __builtin_amdgcn_s_barrier()
; #define PG8_SCHED __builtin_amdgcn_sched_barrier(0)
; template <class Epi>
; __device__ __forceinline__ void gemm_phase(LAS unsigned char* lds, const Gemm g, const int G, const int cidx, const Epi& E) {
;     ...
;             const char* a1 = cA + (size_t)(t + 1) * kstep;
;             const char* a2 = last ? nA : cA + (size_t)(t + 2) * kstep; const char* b2 = last ? nB : cB + (size_t)(t + 2) * kstep;
;             const char* a3 = a2 + kstep; const char* b3 = b2 + kstep;
;             PG8_LDB(B0, 0, 0); PG8_LDB(B1, 0, 1); PG8_SCHED; PG8_LDA(At, 0, 0); PG8_STAGE(PG8_SA(1, 1), a1 + hstep, voffA);
;             PG8_WAIT_V(8); PG8_WAIT_L(0); PG8_BAR; PG8_MMA(0, 0, At, B0); PG8_MMA(0, 1, At, B1); PG8_BAR; PG8_SCHED;
;             PG8_LDA(At, 0, 1); PG8_STAGE(PG8_SB(0, 0), b2, voffB); PG8_STAGE(PG8_SB(0, 1), b2 + hstep, voffB); PG8_STAGE(PG8_SA(0, 0), a2, voffA);
;             PG8_WAIT_V(8); PG8_WAIT_L(0); PG8_BAR; PG8_MMA(1, 0, At, B0); PG8_MMA(1, 1, At, B1); PG8_BAR; PG8_SCHED;
.LBB0_450:
	s_add_u32 s26, s10, s24
	s_addc_u32 s27, s11, s25
	s_add_u32 s26, s26, 0x100
	s_addc_u32 s27, s27, 0
	s_add_u32 s68, s43, s24
	s_addc_u32 s77, s44, s25
	s_add_i32 s83, 0, 0x10000
	s_cmpk_eq_i32 s24, 0x1500
	s_cselect_b32 s29, s21, s27
	s_cselect_b32 s28, s20, s26
	v_add_u32_e32 v3, s83, v157
	s_cselect_b32 s27, s9, s77
	s_cselect_b32 s26, s8, s68
	s_add_i32 s68, 0, 0x14000
	ds_read_b128 v[132:135], v3
	ds_read_b128 v[140:143], v3 offset:1024
	ds_read_b128 v[160:163], v3 offset:2048
	ds_read_b128 v[164:167], v3 offset:3072
	v_add_u32_e32 v3, s68, v157
	ds_read_b128 v[168:171], v3
	ds_read_b128 v[172:175], v3 offset:1024
	ds_read_b128 v[176:179], v3 offset:2048
	ds_read_b128 v[180:183], v3 offset:3072
	v_lshl_add_u64 v[200:201], v[154:155], 0, s[24:25]
	s_add_i32 m0, s71, 0xc000
	ds_read_b128 v[184:187], v159
	ds_read_b128 v[188:191], v159 offset:1024
	ds_read_b128 v[192:195], v159 offset:2048
	ds_read_b128 v[196:199], v159 offset:3072
	ds_read_b128 v[214:217], v159 offset:4096
	ds_read_b128 v[218:221], v159 offset:5120
	ds_read_b128 v[222:225], v159 offset:6144
	ds_read_b128 v[226:229], v159 offset:7168
	global_load_lds_dwordx4 v[200:201], off
	v_lshl_add_u64 v[200:201], v[0:1], 0, s[24:25]
	s_add_i32 m0, s71, 0xe000
	s_nop 0
	global_load_lds_dwordx4 v[200:201], off
	s_waitcnt vmcnt(8)
	s_waitcnt lgkmcnt(0)
	s_barrier
	s_setprio 1
	s_waitcnt lgkmcnt(0)
	v_mfma_f32_16x16x32_bf16 v[100:103], v[132:135], v[184:187], v[100:103]
	v_mfma_f32_16x16x32_bf16 v[108:111], v[160:163], v[184:187], v[108:111]
	v_mfma_f32_16x16x32_bf16 v[120:123], v[132:135], v[192:195], v[120:123]
	v_mfma_f32_16x16x32_bf16 v[128:131], v[160:163], v[192:195], v[128:131]
	v_mfma_f32_16x16x32_bf16 v[96:99], v[132:135], v[214:217], v[96:99]
	v_mfma_f32_16x16x32_bf16 v[92:95], v[160:163], v[214:217], v[92:95]
	v_mfma_f32_16x16x32_bf16 v[80:83], v[132:135], v[222:225], v[80:83]
	v_mfma_f32_16x16x32_bf16 v[76:79], v[160:163], v[222:225], v[76:79]
	v_mfma_f32_16x16x32_bf16 v[100:103], v[140:143], v[188:191], v[100:103]
	v_mfma_f32_16x16x32_bf16 v[108:111], v[164:167], v[188:191], v[108:111]
	v_mfma_f32_16x16x32_bf16 v[120:123], v[140:143], v[196:199], v[120:123]
	v_mfma_f32_16x16x32_bf16 v[128:131], v[164:167], v[196:199], v[128:131]
	v_mfma_f32_16x16x32_bf16 v[96:99], v[140:143], v[218:221], v[96:99]
	v_mfma_f32_16x16x32_bf16 v[92:95], v[164:167], v[218:221], v[92:95]
	v_mfma_f32_16x16x32_bf16 v[80:83], v[140:143], v[226:229], v[80:83]
	v_mfma_f32_16x16x32_bf16 v[76:79], v[164:167], v[226:229], v[76:79]
	s_setprio 0
	s_setprio 1
	v_mfma_f32_16x16x32_bf16 v[116:119], v[168:171], v[184:187], v[116:119]
	v_mfma_f32_16x16x32_bf16 v[124:127], v[176:179], v[184:187], v[124:127]
	v_mfma_f32_16x16x32_bf16 v[112:115], v[168:171], v[192:195], v[112:115]
	v_mfma_f32_16x16x32_bf16 v[104:107], v[176:179], v[192:195], v[104:107]
	v_mfma_f32_16x16x32_bf16 v[88:91], v[168:171], v[214:217], v[88:91]
	v_mfma_f32_16x16x32_bf16 v[84:87], v[176:179], v[214:217], v[84:87]
	v_mfma_f32_16x16x32_bf16 v[72:75], v[168:171], v[222:225], v[72:75]
	v_mfma_f32_16x16x32_bf16 v[68:71], v[176:179], v[222:225], v[68:71]
	v_mfma_f32_16x16x32_bf16 v[116:119], v[172:175], v[188:191], v[116:119]
	v_mfma_f32_16x16x32_bf16 v[124:127], v[180:183], v[188:191], v[124:127]
	v_mfma_f32_16x16x32_bf16 v[112:115], v[172:175], v[196:199], v[112:115]
	v_mfma_f32_16x16x32_bf16 v[104:107], v[180:183], v[196:199], v[104:107]
	v_mfma_f32_16x16x32_bf16 v[88:91], v[172:175], v[218:221], v[88:91]
	v_mfma_f32_16x16x32_bf16 v[84:87], v[180:183], v[218:221], v[84:87]
	v_mfma_f32_16x16x32_bf16 v[72:75], v[172:175], v[226:229], v[72:75]
	v_mfma_f32_16x16x32_bf16 v[68:71], v[180:183], v[226:229], v[68:71]
	s_setprio 0
	s_barrier
	s_sleep 2
	s_add_i32 s77, s83, s70
	v_lshl_add_u64 v[200:201], s[26:27], 0, v[146:147]
	s_mov_b32 m0, s77
	ds_read_b128 v[184:187], v159 offset:16384
	ds_read_b128 v[188:191], v159 offset:17408
	ds_read_b128 v[192:195], v159 offset:18432
	ds_read_b128 v[196:199], v159 offset:19456
	ds_read_b128 v[214:217], v159 offset:20480
	ds_read_b128 v[218:221], v159 offset:21504
	ds_read_b128 v[222:225], v159 offset:22528
	ds_read_b128 v[226:229], v159 offset:23552
	global_load_lds_dwordx4 v[200:201], off
	s_add_i32 m0, s77, 0x2000
	s_add_u32 s86, s26, 0xb0000
	v_lshl_add_u64 v[230:231], s[26:27], 0, v[148:149]
	s_addc_u32 s87, s27, 0
	s_add_i32 s68, s68, s70
	global_load_lds_dwordx4 v[230:231], off
	v_lshl_add_u64 v[232:233], s[86:87], 0, v[146:147]
	s_mov_b32 m0, s68
	v_lshl_add_u64 v[234:235], s[28:29], 0, v[148:149]
	global_load_lds_dwordx4 v[232:233], off
	v_lshl_add_u64 v[232:233], s[86:87], 0, v[148:149]
	s_add_i32 m0, s68, 0x2000
	s_nop 0
	global_load_lds_dwordx4 v[232:233], off
	v_lshl_add_u64 v[232:233], s[28:29], 0, v[146:147]
	s_mov_b32 m0, s71
	s_nop 0
	global_load_lds_dwordx4 v[232:233], off
	s_mov_b32 m0, s72
	s_nop 0
	global_load_lds_dwordx4 v[234:235], off
	s_waitcnt vmcnt(8)
	s_waitcnt lgkmcnt(0)
	s_barrier
; #define PG8_STAGE(bufoff, gbase, voff) do { _Pragma("unroll") for (int _i = 0; _i < 2; ++_i) \
;         __builtin_amdgcn_global_load_lds((const unsigned*)((const char*)(gbase) + (voff)[_i]), (LAS unsigned*)(lds + (bufoff) + ldsw + _i * 8192), 16, 0, 0); } while (0)
; #define PG8_LDA(dst, b, h) do { _Pragma("unroll") for (int m = 0; m < 4; ++m) _Pragma("unroll") for (int k = 0; k < 2; ++k) dst[m][k] = *(const LAS bf16x8*)(lds + PG8_SA(b, h) + aoff + m * 2048 + k * 1024); } while (0)
; #define PG8_LDB(dst, b, h) do { _Pragma("unroll") for (int n = 0; n < 2; ++n) _Pragma("unroll") for (int k = 0; k < 2; ++k) dst[n][k] = *(const LAS bf16x8*)(lds + PG8_SB(b, h) + boff + n * 2048 + k * 1024); } while (0)
; #define PG8_MMA(ai, bj, At, Bt) do { __builtin_amdgcn_s_setprio(1); _Pragma("unroll") for (int m = 0; m < 4; ++m) _Pragma("unroll") for (int n = 0; n < 2; ++n) _Pragma("unroll") for (int k = 0; k < 2; ++k) \
;         acc[ai][bj][m][n] = __builtin_amdgcn_mfma_f32_16x16x32_bf16(Bt[n][k], At[m][k], acc[ai][bj][m][n], 0, 0, 0); __builtin_amdgcn_s_setprio(0); } while (0)
; #define PG8_WAIT_V(n) asm volatile("s_waitcnt vmcnt(" #n ")" ::: "memory")
; #define PG8_WAIT_L(n) asm volatile("s_waitcnt lgkmcnt(" #n ")" ::: "memory")
; #define PG8_BAR __builtin_amdgcn_s_barrier()
; #define PG8_SCHED __builtin_amdgcn_sched_barrier(0)
; template <class Epi>
; __device__ __forceinline__ void gemm_phase(LAS unsigned char* lds, const Gemm g, const int G, const int cidx, const Epi& E) {
;     ...
;             PG8_WAIT_V(8); PG8_WAIT_L(0); PG8_BAR; PG8_MMA(1, 0, At, B0); PG8_MMA(1, 1, At, B1); PG8_BAR; PG8_SCHED;
;             PG8_LDB(B0, 1, 0); PG8_LDB(B1, 1, 1); PG8_SCHED; PG8_LDA(At, 1, 0); PG8_STAGE(PG8_SA(0, 1), a2 + hstep, voffA);
;             PG8_WAIT_V(8); PG8_WAIT_L(0); PG8_BAR; PG8_MMA(0, 0, At, B0); PG8_MMA(0, 1, At, B1); PG8_BAR; PG8_SCHED;
	s_setprio 1
	s_waitcnt lgkmcnt(0)
	v_mfma_f32_16x16x32_bf16 v[64:67], v[132:135], v[184:187], v[64:67]
	v_mfma_f32_16x16x32_bf16 v[60:63], v[160:163], v[184:187], v[60:63]
	v_mfma_f32_16x16x32_bf16 v[48:51], v[132:135], v[192:195], v[48:51]
	v_mfma_f32_16x16x32_bf16 v[44:47], v[160:163], v[192:195], v[44:47]
	v_mfma_f32_16x16x32_bf16 v[32:35], v[132:135], v[214:217], v[32:35]
	v_mfma_f32_16x16x32_bf16 v[28:31], v[160:163], v[214:217], v[28:31]
	v_mfma_f32_16x16x32_bf16 v[16:19], v[132:135], v[222:225], v[16:19]
	v_mfma_f32_16x16x32_bf16 v[12:15], v[160:163], v[222:225], v[12:15]
	v_mfma_f32_16x16x32_bf16 v[64:67], v[140:143], v[188:191], v[64:67]
	v_mfma_f32_16x16x32_bf16 v[60:63], v[164:167], v[188:191], v[60:63]
	v_mfma_f32_16x16x32_bf16 v[48:51], v[140:143], v[196:199], v[48:51]
	v_mfma_f32_16x16x32_bf16 v[44:47], v[164:167], v[196:199], v[44:47]
	v_mfma_f32_16x16x32_bf16 v[32:35], v[140:143], v[218:221], v[32:35]
	v_mfma_f32_16x16x32_bf16 v[28:31], v[164:167], v[218:221], v[28:31]
	v_mfma_f32_16x16x32_bf16 v[16:19], v[140:143], v[226:229], v[16:19]
	v_mfma_f32_16x16x32_bf16 v[12:15], v[164:167], v[226:229], v[12:15]
	s_setprio 0
	s_setprio 1
	v_mfma_f32_16x16x32_bf16 v[56:59], v[168:171], v[184:187], v[56:59]
	v_mfma_f32_16x16x32_bf16 v[52:55], v[176:179], v[184:187], v[52:55]
	v_mfma_f32_16x16x32_bf16 v[40:43], v[168:171], v[192:195], v[40:43]
	v_mfma_f32_16x16x32_bf16 v[36:39], v[176:179], v[192:195], v[36:39]
	v_mfma_f32_16x16x32_bf16 v[24:27], v[168:171], v[214:217], v[24:27]
	v_mfma_f32_16x16x32_bf16 v[20:23], v[176:179], v[214:217], v[20:23]
	v_mfma_f32_16x16x32_bf16 v[8:11], v[168:171], v[222:225], v[8:11]
	v_mfma_f32_16x16x32_bf16 v[4:7], v[176:179], v[222:225], v[4:7]
	v_mfma_f32_16x16x32_bf16 v[56:59], v[172:175], v[188:191], v[56:59]
	v_mfma_f32_16x16x32_bf16 v[52:55], v[180:183], v[188:191], v[52:55]
	v_mfma_f32_16x16x32_bf16 v[40:43], v[172:175], v[196:199], v[40:43]
	v_mfma_f32_16x16x32_bf16 v[36:39], v[180:183], v[196:199], v[36:39]
	v_mfma_f32_16x16x32_bf16 v[24:27], v[172:175], v[218:221], v[24:27]
	v_mfma_f32_16x16x32_bf16 v[20:23], v[180:183], v[218:221], v[20:23]
	v_mfma_f32_16x16x32_bf16 v[8:11], v[172:175], v[226:229], v[8:11]
	v_mfma_f32_16x16x32_bf16 v[4:7], v[180:183], v[226:229], v[4:7]
	s_setprio 0
	s_barrier
	s_sleep 2
	s_add_i32 s68, 0, 0x18000
	v_add_u32_e32 v3, s68, v157
	s_add_i32 s77, 0, 0x1c000
	ds_read_b128 v[132:135], v3
	ds_read_b128 v[140:143], v3 offset:1024
	ds_read_b128 v[160:163], v3 offset:2048
	ds_read_b128 v[164:167], v3 offset:3072
	v_add_u32_e32 v3, s77, v157
	ds_read_b128 v[168:171], v3
	ds_read_b128 v[172:175], v3 offset:1024
	ds_read_b128 v[176:179], v3 offset:2048
	ds_read_b128 v[180:183], v3 offset:3072
	s_add_u32 s28, s28, 0xb0000
	s_addc_u32 s29, s29, 0
	s_mov_b32 m0, s73
	v_lshl_add_u64 v[236:237], s[28:29], 0, v[146:147]
	ds_read_b128 v[184:187], v159 offset:32768
	ds_read_b128 v[188:191], v159 offset:33792
	ds_read_b128 v[192:195], v159 offset:34816
	ds_read_b128 v[196:199], v159 offset:35840
	ds_read_b128 v[214:217], v159 offset:36864
	ds_read_b128 v[218:221], v159 offset:37888
	ds_read_b128 v[222:225], v159 offset:38912
	ds_read_b128 v[226:229], v159 offset:39936
	global_load_lds_dwordx4 v[236:237], off
	v_lshl_add_u64 v[236:237], s[28:29], 0, v[148:149]
	s_mov_b32 m0, s74
	s_nop 0
	global_load_lds_dwordx4 v[236:237], off
	s_waitcnt vmcnt(8)
	s_waitcnt lgkmcnt(0)
	s_barrier
	s_setprio 1
	s_waitcnt lgkmcnt(0)
	v_mfma_f32_16x16x32_bf16 v[100:103], v[132:135], v[184:187], v[100:103]
	v_mfma_f32_16x16x32_bf16 v[108:111], v[160:163], v[184:187], v[108:111]
	v_mfma_f32_16x16x32_bf16 v[120:123], v[132:135], v[192:195], v[120:123]
	v_mfma_f32_16x16x32_bf16 v[128:131], v[160:163], v[192:195], v[128:131]
	v_mfma_f32_16x16x32_bf16 v[96:99], v[132:135], v[214:217], v[96:99]
	v_mfma_f32_16x16x32_bf16 v[92:95], v[160:163], v[214:217], v[92:95]
	v_mfma_f32_16x16x32_bf16 v[80:83], v[132:135], v[222:225], v[80:83]
	v_mfma_f32_16x16x32_bf16 v[76:79], v[160:163], v[222:225], v[76:79]
	v_mfma_f32_16x16x32_bf16 v[100:103], v[140:143], v[188:191], v[100:103]
	v_mfma_f32_16x16x32_bf16 v[108:111], v[164:167], v[188:191], v[108:111]
	v_mfma_f32_16x16x32_bf16 v[120:123], v[140:143], v[196:199], v[120:123]
	v_mfma_f32_16x16x32_bf16 v[128:131], v[164:167], v[196:199], v[128:131]
	v_mfma_f32_16x16x32_bf16 v[96:99], v[140:143], v[218:221], v[96:99]
	v_mfma_f32_16x16x32_bf16 v[92:95], v[164:167], v[218:221], v[92:95]
	v_mfma_f32_16x16x32_bf16 v[80:83], v[140:143], v[226:229], v[80:83]
	v_mfma_f32_16x16x32_bf16 v[76:79], v[164:167], v[226:229], v[76:79]
	s_setprio 0
	s_setprio 1
	v_mfma_f32_16x16x32_bf16 v[116:119], v[168:171], v[184:187], v[116:119]
	v_mfma_f32_16x16x32_bf16 v[124:127], v[176:179], v[184:187], v[124:127]
	v_mfma_f32_16x16x32_bf16 v[112:115], v[168:171], v[192:195], v[112:115]
	v_mfma_f32_16x16x32_bf16 v[104:107], v[176:179], v[192:195], v[104:107]
	v_mfma_f32_16x16x32_bf16 v[88:91], v[168:171], v[214:217], v[88:91]
	v_mfma_f32_16x16x32_bf16 v[84:87], v[176:179], v[214:217], v[84:87]
	v_mfma_f32_16x16x32_bf16 v[72:75], v[168:171], v[222:225], v[72:75]
	v_mfma_f32_16x16x32_bf16 v[68:71], v[176:179], v[222:225], v[68:71]
	v_mfma_f32_16x16x32_bf16 v[116:119], v[172:175], v[188:191], v[116:119]
	v_mfma_f32_16x16x32_bf16 v[124:127], v[180:183], v[188:191], v[124:127]
	v_mfma_f32_16x16x32_bf16 v[112:115], v[172:175], v[196:199], v[112:115]
	v_mfma_f32_16x16x32_bf16 v[104:107], v[180:183], v[196:199], v[104:107]
	v_mfma_f32_16x16x32_bf16 v[88:91], v[172:175], v[218:221], v[88:91]
	v_mfma_f32_16x16x32_bf16 v[84:87], v[180:183], v[218:221], v[84:87]
	v_mfma_f32_16x16x32_bf16 v[72:75], v[172:175], v[226:229], v[72:75]
	v_mfma_f32_16x16x32_bf16 v[68:71], v[180:183], v[226:229], v[68:71]
	s_setprio 0
	s_barrier
; #define PG8_STAGE(bufoff, gbase, voff) do { _Pragma("unroll") for (int _i = 0; _i < 2; ++_i) \
;         __builtin_amdgcn_global_load_lds((const unsigned*)((const char*)(gbase) + (voff)[_i]), (LAS unsigned*)(lds + (bufoff) + ldsw + _i * 8192), 16, 0, 0); } while (0)
; #define PG8_LDA(dst, b, h) do { _Pragma("unroll") for (int m = 0; m < 4; ++m) _Pragma("unroll") for (int k = 0; k < 2; ++k) dst[m][k] = *(const LAS bf16x8*)(lds + PG8_SA(b, h) + aoff + m * 2048 + k * 1024); } while (0)
; #define PG8_MMA(ai, bj, At, Bt) do { __builtin_amdgcn_s_setprio(1); _Pragma("unroll") for (int m = 0; m < 4; ++m) _Pragma("unroll") for (int n = 0; n < 2; ++n) _Pragma("unroll") for (int k = 0; k < 2; ++k) \
;         acc[ai][bj][m][n] = __builtin_amdgcn_mfma_f32_16x16x32_bf16(Bt[n][k], At[m][k], acc[ai][bj][m][n], 0, 0, 0); __builtin_amdgcn_s_setprio(0); } while (0)
; #define PG8_WAIT_V(n) asm volatile("s_waitcnt vmcnt(" #n ")" ::: "memory")
; #define PG8_WAIT_L(n) asm volatile("s_waitcnt lgkmcnt(" #n ")" ::: "memory")
; #define PG8_BAR __builtin_amdgcn_s_barrier()
; #define PG8_SCHED __builtin_amdgcn_sched_barrier(0)
; template <class Epi>
; __device__ __forceinline__ void gemm_phase(LAS unsigned char* lds, const Gemm g, const int G, const int cidx, const Epi& E) {
;     ...
;             PG8_LDA(At, 1, 1); PG8_STAGE(PG8_SB(1, 0), b3, voffB); PG8_STAGE(PG8_SB(1, 1), b3 + hstep, voffB); PG8_STAGE(PG8_SA(1, 0), a3, voffA);
;             PG8_WAIT_V(8); PG8_WAIT_L(0); PG8_BAR; PG8_MMA(1, 0, At, B0); PG8_MMA(1, 1, At, B1); PG8_BAR; PG8_SCHED;
;         }
;         if constexpr (!Epi::AFTER_DRAIN) E(acc, cur, wr, wc, fr, fq);
;         if (!has_next) break;
; #pragma unroll
;         for (int a = 0; a < 2; ++a)
; #pragma unroll
;             for (int b = 0; b < 2; ++b)
; #pragma unroll
;                 for (int m = 0; m < 4; ++m)
; #pragma unroll
;                     for (int n = 0; n < 2; ++n) acc[a][b][m][n] = ZERO4;
;         cur = nxt; cA = nA; cB = nB; ++ui;
	s_sleep 2
	s_add_i32 s28, s68, s70
	v_lshl_add_u64 v[200:201], v[200:201], 0, s[46:47]
	s_mov_b32 m0, s28
	ds_read_b128 v[184:187], v159 offset:49152
	ds_read_b128 v[188:191], v159 offset:50176
	ds_read_b128 v[192:195], v159 offset:51200
	ds_read_b128 v[196:199], v159 offset:52224
	ds_read_b128 v[214:217], v159 offset:53248
	ds_read_b128 v[218:221], v159 offset:54272
	ds_read_b128 v[222:225], v159 offset:55296
	ds_read_b128 v[226:229], v159 offset:56320
	global_load_lds_dwordx4 v[200:201], off
	s_add_i32 m0, s28, 0x2000
	s_add_u32 s26, s26, 0xb0080
	v_lshl_add_u64 v[200:201], v[230:231], 0, s[46:47]
	s_addc_u32 s27, s27, 0
	s_add_i32 s28, s77, s70
	global_load_lds_dwordx4 v[200:201], off
	v_lshl_add_u64 v[200:201], s[26:27], 0, v[146:147]
	s_mov_b32 m0, s28
	s_nop 0
	global_load_lds_dwordx4 v[200:201], off
	v_lshl_add_u64 v[200:201], s[26:27], 0, v[148:149]
	s_add_i32 m0, s28, 0x2000
	s_nop 0
	global_load_lds_dwordx4 v[200:201], off
	v_lshl_add_u64 v[200:201], v[232:233], 0, s[46:47]
	s_mov_b32 m0, s75
	s_nop 0
	global_load_lds_dwordx4 v[200:201], off
	v_lshl_add_u64 v[200:201], v[234:235], 0, s[46:47]
	s_mov_b32 m0, s76
	s_nop 0
	global_load_lds_dwordx4 v[200:201], off
	s_waitcnt vmcnt(8)
	s_waitcnt lgkmcnt(0)
	s_barrier
	s_setprio 1
	s_waitcnt lgkmcnt(0)
	v_mfma_f32_16x16x32_bf16 v[64:67], v[132:135], v[184:187], v[64:67]
	v_mfma_f32_16x16x32_bf16 v[60:63], v[160:163], v[184:187], v[60:63]
	v_mfma_f32_16x16x32_bf16 v[48:51], v[132:135], v[192:195], v[48:51]
	v_mfma_f32_16x16x32_bf16 v[44:47], v[160:163], v[192:195], v[44:47]
	v_mfma_f32_16x16x32_bf16 v[32:35], v[132:135], v[214:217], v[32:35]
	v_mfma_f32_16x16x32_bf16 v[28:31], v[160:163], v[214:217], v[28:31]
	v_mfma_f32_16x16x32_bf16 v[16:19], v[132:135], v[222:225], v[16:19]
	v_mfma_f32_16x16x32_bf16 v[12:15], v[160:163], v[222:225], v[12:15]
	v_mfma_f32_16x16x32_bf16 v[64:67], v[140:143], v[188:191], v[64:67]
	v_mfma_f32_16x16x32_bf16 v[60:63], v[164:167], v[188:191], v[60:63]
	v_mfma_f32_16x16x32_bf16 v[48:51], v[140:143], v[196:199], v[48:51]
	v_mfma_f32_16x16x32_bf16 v[44:47], v[164:167], v[196:199], v[44:47]
	v_mfma_f32_16x16x32_bf16 v[32:35], v[140:143], v[218:221], v[32:35]
	v_mfma_f32_16x16x32_bf16 v[28:31], v[164:167], v[218:221], v[28:31]
	v_mfma_f32_16x16x32_bf16 v[16:19], v[140:143], v[226:229], v[16:19]
	v_mfma_f32_16x16x32_bf16 v[12:15], v[164:167], v[226:229], v[12:15]
	s_setprio 0
	s_setprio 1
	v_mfma_f32_16x16x32_bf16 v[56:59], v[168:171], v[184:187], v[56:59]
	v_mfma_f32_16x16x32_bf16 v[52:55], v[176:179], v[184:187], v[52:55]
	v_mfma_f32_16x16x32_bf16 v[40:43], v[168:171], v[192:195], v[40:43]
	v_mfma_f32_16x16x32_bf16 v[36:39], v[176:179], v[192:195], v[36:39]
	v_mfma_f32_16x16x32_bf16 v[24:27], v[168:171], v[214:217], v[24:27]
	v_mfma_f32_16x16x32_bf16 v[20:23], v[176:179], v[214:217], v[20:23]
	v_mfma_f32_16x16x32_bf16 v[8:11], v[168:171], v[222:225], v[8:11]
	v_mfma_f32_16x16x32_bf16 v[4:7], v[176:179], v[222:225], v[4:7]
	v_mfma_f32_16x16x32_bf16 v[56:59], v[172:175], v[188:191], v[56:59]
	v_mfma_f32_16x16x32_bf16 v[52:55], v[180:183], v[188:191], v[52:55]
	v_mfma_f32_16x16x32_bf16 v[40:43], v[172:175], v[196:199], v[40:43]
	v_mfma_f32_16x16x32_bf16 v[36:39], v[180:183], v[196:199], v[36:39]
	v_mfma_f32_16x16x32_bf16 v[24:27], v[172:175], v[218:221], v[24:27]
	v_mfma_f32_16x16x32_bf16 v[20:23], v[180:183], v[218:221], v[20:23]
	v_mfma_f32_16x16x32_bf16 v[8:11], v[172:175], v[226:229], v[8:11]
	v_mfma_f32_16x16x32_bf16 v[4:7], v[180:183], v[226:229], v[4:7]
	s_setprio 0
	s_barrier
	s_sleep 2
	s_add_i32 s45, s45, 2
	s_add_u32 s24, s24, 0x100
	s_addc_u32 s25, s25, 0
	s_cmp_gt_u32 s45, 41
	s_cbranch_scc0 .LBB0_450
	s_add_u32 s24, s43, 0xffffff00
	s_addc_u32 s25, s44, -1
	s_and_b64 vcc, exec, s[6:7]
	s_cbranch_vccnz .LBB0_453
	v_mov_b32_e32 v4, 0
	s_mov_b32 s14, s84
	s_mov_b32 s35, s88
	s_mov_b64 s[10:11], s[20:21]
	s_mov_b32 s79, s33
	v_mov_b32_e32 v5, v4
	v_mov_b32_e32 v6, v4
	v_mov_b32_e32 v7, v4
	v_mov_b32_e32 v8, v4
	v_mov_b32_e32 v9, v4
	v_mov_b32_e32 v10, v4
	v_mov_b32_e32 v11, v4
	v_mov_b32_e32 v20, v4
	v_mov_b32_e32 v21, v4
	v_mov_b32_e32 v22, v4
	v_mov_b32_e32 v23, v4
	v_mov_b32_e32 v24, v4
	v_mov_b32_e32 v25, v4
	v_mov_b32_e32 v26, v4
	v_mov_b32_e32 v27, v4
	v_mov_b32_e32 v36, v4
	v_mov_b32_e32 v37, v4
	v_mov_b32_e32 v38, v4
	v_mov_b32_e32 v39, v4
	v_mov_b32_e32 v40, v4
	v_mov_b32_e32 v41, v4
	v_mov_b32_e32 v42, v4
	v_mov_b32_e32 v43, v4
	v_mov_b32_e32 v52, v4
	v_mov_b32_e32 v53, v4
	v_mov_b32_e32 v54, v4
	v_mov_b32_e32 v55, v4
	v_mov_b32_e32 v56, v4
	v_mov_b32_e32 v57, v4
	v_mov_b32_e32 v58, v4
	v_mov_b32_e32 v59, v4
	v_mov_b32_e32 v12, v4
	v_mov_b32_e32 v13, v4
	v_mov_b32_e32 v14, v4
	v_mov_b32_e32 v15, v4
	v_mov_b32_e32 v16, v4
	v_mov_b32_e32 v17, v4
	v_mov_b32_e32 v18, v4
	v_mov_b32_e32 v19, v4
	v_mov_b32_e32 v28, v4
	v_mov_b32_e32 v29, v4
	v_mov_b32_e32 v30, v4
	v_mov_b32_e32 v31, v4
	v_mov_b32_e32 v32, v4
	v_mov_b32_e32 v33, v4
	v_mov_b32_e32 v34, v4
	v_mov_b32_e32 v35, v4
	v_mov_b32_e32 v44, v4
	v_mov_b32_e32 v45, v4
	v_mov_b32_e32 v46, v4
	v_mov_b32_e32 v47, v4
	v_mov_b32_e32 v48, v4
	v_mov_b32_e32 v49, v4
	v_mov_b32_e32 v50, v4
	v_mov_b32_e32 v51, v4
	v_mov_b32_e32 v60, v4
	v_mov_b32_e32 v61, v4
	v_mov_b32_e32 v62, v4
	v_mov_b32_e32 v63, v4
	v_mov_b32_e32 v64, v4
	v_mov_b32_e32 v65, v4
	v_mov_b32_e32 v66, v4
	v_mov_b32_e32 v67, v4
	v_mov_b32_e32 v68, v4
	v_mov_b32_e32 v69, v4
	v_mov_b32_e32 v70, v4
	v_mov_b32_e32 v71, v4
	v_mov_b32_e32 v72, v4
	v_mov_b32_e32 v73, v4
	v_mov_b32_e32 v74, v4
	v_mov_b32_e32 v75, v4
	v_mov_b32_e32 v84, v4
	v_mov_b32_e32 v85, v4
	v_mov_b32_e32 v86, v4
	v_mov_b32_e32 v87, v4
	v_mov_b32_e32 v88, v4
	v_mov_b32_e32 v89, v4
	v_mov_b32_e32 v90, v4
	v_mov_b32_e32 v91, v4
	v_mov_b32_e32 v104, v4
	v_mov_b32_e32 v105, v4
	v_mov_b32_e32 v106, v4
	v_mov_b32_e32 v107, v4
	v_mov_b32_e32 v112, v4
	v_mov_b32_e32 v113, v4
	v_mov_b32_e32 v114, v4
	v_mov_b32_e32 v115, v4
	v_mov_b32_e32 v124, v4
	v_mov_b32_e32 v125, v4
	v_mov_b32_e32 v126, v4
	v_mov_b32_e32 v127, v4
	v_mov_b32_e32 v116, v4
	v_mov_b32_e32 v117, v4
	v_mov_b32_e32 v118, v4
	v_mov_b32_e32 v119, v4
	v_mov_b32_e32 v76, v4
	v_mov_b32_e32 v77, v4
	v_mov_b32_e32 v78, v4
	v_mov_b32_e32 v79, v4
	v_mov_b32_e32 v80, v4
	v_mov_b32_e32 v81, v4
	v_mov_b32_e32 v82, v4
	v_mov_b32_e32 v83, v4
	v_mov_b32_e32 v92, v4
	v_mov_b32_e32 v93, v4
	v_mov_b32_e32 v94, v4
	v_mov_b32_e32 v95, v4
	v_mov_b32_e32 v96, v4
	v_mov_b32_e32 v97, v4
	v_mov_b32_e32 v98, v4
	v_mov_b32_e32 v99, v4
	v_mov_b32_e32 v128, v4
	v_mov_b32_e32 v129, v4
	v_mov_b32_e32 v130, v4
	v_mov_b32_e32 v131, v4
	v_mov_b32_e32 v120, v4
	v_mov_b32_e32 v121, v4
	v_mov_b32_e32 v122, v4
	v_mov_b32_e32 v123, v4
	v_mov_b32_e32 v108, v4
	v_mov_b32_e32 v109, v4
	v_mov_b32_e32 v110, v4
	v_mov_b32_e32 v111, v4
	v_mov_b32_e32 v100, v4
	v_mov_b32_e32 v101, v4
	v_mov_b32_e32 v102, v4
	v_mov_b32_e32 v103, v4
	s_mov_b32 s83, 0x18000
	s_mov_b32 s86, 0x3fb8aa3b
	s_andn2_b64 vcc, exec, s[4:5]
	s_cbranch_vccnz .LBB0_454
	s_branch .LBB0_455

; #define PG8_STAGE(bufoff, gbase, voff) do { _Pragma("unroll") for (int _i = 0; _i < 2; ++_i) \
;         __builtin_amdgcn_global_load_lds((const unsigned*)((const char*)(gbase) + (voff)[_i]), (LAS unsigned*)(lds + (bufoff) + ldsw + _i * 8192), 16, 0, 0); } while (0)
; #define PG8_LDA(dst, b, h) do { _Pragma("unroll") for (int m = 0; m < 4; ++m) _Pragma("unroll") for (int k = 0; k < 2; ++k) dst[m][k] = *(const LAS bf16x8*)(lds + PG8_SA(b, h) + aoff + m * 2048 + k * 1024); } while (0)
; #define PG8_LDB(dst, b, h) do { _Pragma("unroll") for (int n = 0; n < 2; ++n) _Pragma("unroll") for (int k = 0; k < 2; ++k) dst[n][k] = *(const LAS bf16x8*)(lds + PG8_SB(b, h) + boff + n * 2048 + k * 1024); } while (0)
; #define PG8_MMA(ai, bj, At, Bt) do { __builtin_amdgcn_s_setprio(1); _Pragma("unroll") for (int m = 0; m < 4; ++m) _Pragma("unroll") for (int n = 0; n < 2; ++n) _Pragma("unroll") for (int k = 0; k < 2; ++k) \
;         acc[ai][bj][m][n] = __builtin_amdgcn_mfma_f32_16x16x32_bf16(Bt[n][k], At[m][k], acc[ai][bj][m][n], 0, 0, 0); __builtin_amdgcn_s_setprio(0); } while (0)
; #define PG8_WAIT_V(n) asm volatile("s_waitcnt vmcnt(" #n ")" ::: "memory")
; #define PG8_WAIT_L(n) asm volatile("s_waitcnt lgkmcnt(" #n ")" ::: "memory")
; #define PG8_BAR __builtin_amdgcn_s_barrier()
; #define PG8_SCHED __builtin_amdgcn_sched_barrier(0)
; template <class Epi>
; __device__ __forceinline__ void gemm_phase(LAS unsigned char* lds, const Gemm g, const int G, const int cidx, const Epi& E) {
;     ...
;             const char* a1 = cA + (size_t)(t + 1) * kstep;
;             const char* a2 = last ? nA : cA + (size_t)(t + 2) * kstep; const char* b2 = last ? nB : cB + (size_t)(t + 2) * kstep;
;             const char* a3 = a2 + kstep; const char* b3 = b2 + kstep;
;             PG8_LDB(B0, 0, 0); PG8_LDB(B1, 0, 1); PG8_SCHED; PG8_LDA(At, 0, 0); PG8_STAGE(PG8_SA(1, 1), a1 + hstep, voffA);
;             PG8_WAIT_V(8); PG8_WAIT_L(0); PG8_BAR; PG8_MMA(0, 0, At, B0); PG8_MMA(0, 1, At, B1); PG8_BAR; PG8_SCHED;
;             PG8_LDA(At, 0, 1); PG8_STAGE(PG8_SB(0, 0), b2, voffB); PG8_STAGE(PG8_SB(0, 1), b2 + hstep, voffB); PG8_STAGE(PG8_SA(0, 0), a2, voffA);
.LBB0_601:
	s_add_u32 s24, s20, 0xfffc0080
	s_addc_u32 s25, s21, -1
	s_add_i32 s43, 0, 0x10000
	s_cmp_eq_u32 s45, 12
	s_cselect_b32 s27, s11, s25
	s_cselect_b32 s26, s19, s24
	v_add_u32_e32 v132, s43, v145
	s_cselect_b32 s25, s9, s44
	s_cselect_b32 s24, s33, s42
	s_add_i32 s68, 0, 0x14000
	ds_read_b128 v[158:161], v132
	ds_read_b128 v[164:167], v132 offset:1024
	ds_read_b128 v[168:171], v132 offset:2048
	ds_read_b128 v[172:175], v132 offset:3072
	v_add_u32_e32 v132, s68, v145
	ds_read_b128 v[176:179], v132
	ds_read_b128 v[180:183], v132 offset:1024
	ds_read_b128 v[184:187], v132 offset:2048
	ds_read_b128 v[188:191], v132 offset:3072
	v_lshl_add_u64 v[132:133], s[20:21], 0, v[156:157]
	s_add_i32 m0, s97, 0xc000
	ds_read_b128 v[192:195], v163
	ds_read_b128 v[196:199], v163 offset:1024
	ds_read_b128 v[214:217], v163 offset:2048
	ds_read_b128 v[218:221], v163 offset:3072
	ds_read_b128 v[222:225], v163 offset:4096
	ds_read_b128 v[226:229], v163 offset:5120
	ds_read_b128 v[230:233], v163 offset:6144
	ds_read_b128 v[234:237], v163 offset:7168
	global_load_lds_dwordx4 v[132:133], off
	v_lshl_add_u64 v[132:133], s[20:21], 0, v[154:155]
	s_add_i32 m0, s97, 0xe000
	s_nop 0
	global_load_lds_dwordx4 v[132:133], off
	s_waitcnt vmcnt(8)
	s_waitcnt lgkmcnt(0)
	s_barrier
	s_setprio 1
	s_waitcnt lgkmcnt(0)
	v_mfma_f32_16x16x32_bf16 v[128:131], v[158:161], v[192:195], v[128:131]
	v_mfma_f32_16x16x32_bf16 v[124:127], v[168:171], v[192:195], v[124:127]
	v_mfma_f32_16x16x32_bf16 v[120:123], v[158:161], v[214:217], v[120:123]
	v_mfma_f32_16x16x32_bf16 v[112:115], v[168:171], v[214:217], v[112:115]
	v_mfma_f32_16x16x32_bf16 v[104:107], v[158:161], v[222:225], v[104:107]
	v_mfma_f32_16x16x32_bf16 v[96:99], v[168:171], v[222:225], v[96:99]
	v_mfma_f32_16x16x32_bf16 v[88:91], v[158:161], v[230:233], v[88:91]
	v_mfma_f32_16x16x32_bf16 v[80:83], v[168:171], v[230:233], v[80:83]
	v_mfma_f32_16x16x32_bf16 v[128:131], v[164:167], v[196:199], v[128:131]
	v_mfma_f32_16x16x32_bf16 v[124:127], v[172:175], v[196:199], v[124:127]
	v_mfma_f32_16x16x32_bf16 v[120:123], v[164:167], v[218:221], v[120:123]
	v_mfma_f32_16x16x32_bf16 v[112:115], v[172:175], v[218:221], v[112:115]
	v_mfma_f32_16x16x32_bf16 v[104:107], v[164:167], v[226:229], v[104:107]
	v_mfma_f32_16x16x32_bf16 v[96:99], v[172:175], v[226:229], v[96:99]
	v_mfma_f32_16x16x32_bf16 v[88:91], v[164:167], v[234:237], v[88:91]
	v_mfma_f32_16x16x32_bf16 v[80:83], v[172:175], v[234:237], v[80:83]
	s_setprio 0
	s_setprio 1
	v_mfma_f32_16x16x32_bf16 v[116:119], v[176:179], v[192:195], v[116:119]
	v_mfma_f32_16x16x32_bf16 v[108:111], v[184:187], v[192:195], v[108:111]
	v_mfma_f32_16x16x32_bf16 v[100:103], v[176:179], v[214:217], v[100:103]
	v_mfma_f32_16x16x32_bf16 v[92:95], v[184:187], v[214:217], v[92:95]
	v_mfma_f32_16x16x32_bf16 v[84:87], v[176:179], v[222:225], v[84:87]
	v_mfma_f32_16x16x32_bf16 v[76:79], v[184:187], v[222:225], v[76:79]
	v_mfma_f32_16x16x32_bf16 v[72:75], v[176:179], v[230:233], v[72:75]
	v_mfma_f32_16x16x32_bf16 v[68:71], v[184:187], v[230:233], v[68:71]
	v_mfma_f32_16x16x32_bf16 v[116:119], v[180:183], v[196:199], v[116:119]
	v_mfma_f32_16x16x32_bf16 v[108:111], v[188:191], v[196:199], v[108:111]
	v_mfma_f32_16x16x32_bf16 v[100:103], v[180:183], v[218:221], v[100:103]
	v_mfma_f32_16x16x32_bf16 v[92:95], v[188:191], v[218:221], v[92:95]
	v_mfma_f32_16x16x32_bf16 v[84:87], v[180:183], v[226:229], v[84:87]
	v_mfma_f32_16x16x32_bf16 v[76:79], v[188:191], v[226:229], v[76:79]
	v_mfma_f32_16x16x32_bf16 v[72:75], v[180:183], v[234:237], v[72:75]
	v_mfma_f32_16x16x32_bf16 v[68:71], v[188:191], v[234:237], v[68:71]
	s_setprio 0
	s_barrier
	s_sleep 2
	s_add_i32 s43, s43, s95
	v_lshl_add_u64 v[132:133], s[24:25], 0, v[148:149]
	s_mov_b32 m0, s43
	ds_read_b128 v[192:195], v163 offset:16384
	ds_read_b128 v[196:199], v163 offset:17408
	ds_read_b128 v[214:217], v163 offset:18432
	ds_read_b128 v[218:221], v163 offset:19456
	ds_read_b128 v[222:225], v163 offset:20480
	ds_read_b128 v[226:229], v163 offset:21504
	ds_read_b128 v[230:233], v163 offset:22528
	ds_read_b128 v[234:237], v163 offset:23552
	global_load_lds_dwordx4 v[132:133], off
	s_add_i32 m0, s43, 0x2000
	s_add_u32 s86, s24, 0x40000
	v_lshl_add_u64 v[134:135], s[24:25], 0, v[0:1]
	s_addc_u32 s87, s25, 0
	s_add_i32 s43, s68, s95
	global_load_lds_dwordx4 v[134:135], off
	v_lshl_add_u64 v[140:141], s[86:87], 0, v[148:149]
	s_mov_b32 m0, s43
	v_lshl_add_u64 v[142:143], s[26:27], 0, v[146:147]
	global_load_lds_dwordx4 v[140:141], off
	v_lshl_add_u64 v[140:141], s[86:87], 0, v[0:1]
	s_add_i32 m0, s43, 0x2000
	s_nop 0
	global_load_lds_dwordx4 v[140:141], off
	v_lshl_add_u64 v[140:141], s[26:27], 0, v[150:151]
	s_mov_b32 m0, s97
	s_nop 0
	global_load_lds_dwordx4 v[140:141], off
	s_mov_b32 m0, s22
	s_nop 0
	global_load_lds_dwordx4 v[142:143], off
	s_waitcnt vmcnt(8)
	s_waitcnt lgkmcnt(0)
	s_barrier
; #define PG8_STAGE(bufoff, gbase, voff) do { _Pragma("unroll") for (int _i = 0; _i < 2; ++_i) \
;         __builtin_amdgcn_global_load_lds((const unsigned*)((const char*)(gbase) + (voff)[_i]), (LAS unsigned*)(lds + (bufoff) + ldsw + _i * 8192), 16, 0, 0); } while (0)
; #define PG8_LDA(dst, b, h) do { _Pragma("unroll") for (int m = 0; m < 4; ++m) _Pragma("unroll") for (int k = 0; k < 2; ++k) dst[m][k] = *(const LAS bf16x8*)(lds + PG8_SA(b, h) + aoff + m * 2048 + k * 1024); } while (0)
; #define PG8_LDB(dst, b, h) do { _Pragma("unroll") for (int n = 0; n < 2; ++n) _Pragma("unroll") for (int k = 0; k < 2; ++k) dst[n][k] = *(const LAS bf16x8*)(lds + PG8_SB(b, h) + boff + n * 2048 + k * 1024); } while (0)
; #define PG8_MMA(ai, bj, At, Bt) do { __builtin_amdgcn_s_setprio(1); _Pragma("unroll") for (int m = 0; m < 4; ++m) _Pragma("unroll") for (int n = 0; n < 2; ++n) _Pragma("unroll") for (int k = 0; k < 2; ++k) \
;         acc[ai][bj][m][n] = __builtin_amdgcn_mfma_f32_16x16x32_bf16(Bt[n][k], At[m][k], acc[ai][bj][m][n], 0, 0, 0); __builtin_amdgcn_s_setprio(0); } while (0)
; #define PG8_WAIT_V(n) asm volatile("s_waitcnt vmcnt(" #n ")" ::: "memory")
; #define PG8_WAIT_L(n) asm volatile("s_waitcnt lgkmcnt(" #n ")" ::: "memory")
; #define PG8_BAR __builtin_amdgcn_s_barrier()
; #define PG8_SCHED __builtin_amdgcn_sched_barrier(0)
; template <class Epi>
; __device__ __forceinline__ void gemm_phase(LAS unsigned char* lds, const Gemm g, const int G, const int cidx, const Epi& E) {
;     ...
;             PG8_WAIT_V(8); PG8_WAIT_L(0); PG8_BAR; PG8_MMA(1, 0, At, B0); PG8_MMA(1, 1, At, B1); PG8_BAR; PG8_SCHED;
;             PG8_LDB(B0, 1, 0); PG8_LDB(B1, 1, 1); PG8_SCHED; PG8_LDA(At, 1, 0); PG8_STAGE(PG8_SA(0, 1), a2 + hstep, voffA);
;             PG8_WAIT_V(8); PG8_WAIT_L(0); PG8_BAR; PG8_MMA(0, 0, At, B0); PG8_MMA(0, 1, At, B1); PG8_BAR; PG8_SCHED;
	s_setprio 1
	s_waitcnt lgkmcnt(0)
	v_mfma_f32_16x16x32_bf16 v[64:67], v[158:161], v[192:195], v[64:67]
	v_mfma_f32_16x16x32_bf16 v[60:63], v[168:171], v[192:195], v[60:63]
	v_mfma_f32_16x16x32_bf16 v[56:59], v[158:161], v[214:217], v[56:59]
	v_mfma_f32_16x16x32_bf16 v[48:51], v[168:171], v[214:217], v[48:51]
	v_mfma_f32_16x16x32_bf16 v[40:43], v[158:161], v[222:225], v[40:43]
	v_mfma_f32_16x16x32_bf16 v[32:35], v[168:171], v[222:225], v[32:35]
	v_mfma_f32_16x16x32_bf16 v[24:27], v[158:161], v[230:233], v[24:27]
	v_mfma_f32_16x16x32_bf16 v[16:19], v[168:171], v[230:233], v[16:19]
	v_mfma_f32_16x16x32_bf16 v[64:67], v[164:167], v[196:199], v[64:67]
	v_mfma_f32_16x16x32_bf16 v[60:63], v[172:175], v[196:199], v[60:63]
	v_mfma_f32_16x16x32_bf16 v[56:59], v[164:167], v[218:221], v[56:59]
	v_mfma_f32_16x16x32_bf16 v[48:51], v[172:175], v[218:221], v[48:51]
	v_mfma_f32_16x16x32_bf16 v[40:43], v[164:167], v[226:229], v[40:43]
	v_mfma_f32_16x16x32_bf16 v[32:35], v[172:175], v[226:229], v[32:35]
	v_mfma_f32_16x16x32_bf16 v[24:27], v[164:167], v[234:237], v[24:27]
	v_mfma_f32_16x16x32_bf16 v[16:19], v[172:175], v[234:237], v[16:19]
	s_setprio 0
	s_setprio 1
	v_mfma_f32_16x16x32_bf16 v[52:55], v[176:179], v[192:195], v[52:55]
	v_mfma_f32_16x16x32_bf16 v[44:47], v[184:187], v[192:195], v[44:47]
	v_mfma_f32_16x16x32_bf16 v[36:39], v[176:179], v[214:217], v[36:39]
	v_mfma_f32_16x16x32_bf16 v[28:31], v[184:187], v[214:217], v[28:31]
	v_mfma_f32_16x16x32_bf16 v[20:23], v[176:179], v[222:225], v[20:23]
	v_mfma_f32_16x16x32_bf16 v[12:15], v[184:187], v[222:225], v[12:15]
	v_mfma_f32_16x16x32_bf16 v[8:11], v[176:179], v[230:233], v[8:11]
	v_mfma_f32_16x16x32_bf16 v[4:7], v[184:187], v[230:233], v[4:7]
	v_mfma_f32_16x16x32_bf16 v[52:55], v[180:183], v[196:199], v[52:55]
	v_mfma_f32_16x16x32_bf16 v[44:47], v[188:191], v[196:199], v[44:47]
	v_mfma_f32_16x16x32_bf16 v[36:39], v[180:183], v[218:221], v[36:39]
	v_mfma_f32_16x16x32_bf16 v[28:31], v[188:191], v[218:221], v[28:31]
	v_mfma_f32_16x16x32_bf16 v[20:23], v[180:183], v[226:229], v[20:23]
	v_mfma_f32_16x16x32_bf16 v[12:15], v[188:191], v[226:229], v[12:15]
	v_mfma_f32_16x16x32_bf16 v[8:11], v[180:183], v[234:237], v[8:11]
	v_mfma_f32_16x16x32_bf16 v[4:7], v[188:191], v[234:237], v[4:7]
	s_setprio 0
	s_barrier
	s_sleep 2
	s_add_i32 s43, 0, 0x18000
	s_add_i32 s68, 0, 0x1c000
	v_add_u32_e32 v172, s43, v145
	v_add_u32_e32 v188, s68, v145
	ds_read_b128 v[158:161], v172
	ds_read_b128 v[164:167], v172 offset:1024
	ds_read_b128 v[168:171], v172 offset:2048
	ds_read_b128 v[172:175], v172 offset:3072
	ds_read_b128 v[176:179], v188
	ds_read_b128 v[180:183], v188 offset:1024
	ds_read_b128 v[184:187], v188 offset:2048
	ds_read_b128 v[188:191], v188 offset:3072
	s_add_u32 s26, s26, 0x40000
	s_addc_u32 s27, s27, 0
	s_mov_b32 m0, s16
	v_lshl_add_u64 v[200:201], s[26:27], 0, v[150:151]
	ds_read_b128 v[192:195], v163 offset:32768
	ds_read_b128 v[196:199], v163 offset:33792
	ds_read_b128 v[214:217], v163 offset:34816
	ds_read_b128 v[218:221], v163 offset:35840
	ds_read_b128 v[222:225], v163 offset:36864
	ds_read_b128 v[226:229], v163 offset:37888
	ds_read_b128 v[230:233], v163 offset:38912
	ds_read_b128 v[234:237], v163 offset:39936
	global_load_lds_dwordx4 v[200:201], off
	v_lshl_add_u64 v[200:201], s[26:27], 0, v[146:147]
	s_mov_b32 m0, s17
	s_nop 0
	global_load_lds_dwordx4 v[200:201], off
	s_waitcnt vmcnt(8)
	s_waitcnt lgkmcnt(0)
	s_barrier
	s_setprio 1
	s_waitcnt lgkmcnt(0)
	v_mfma_f32_16x16x32_bf16 v[128:131], v[158:161], v[192:195], v[128:131]
	v_mfma_f32_16x16x32_bf16 v[124:127], v[168:171], v[192:195], v[124:127]
	v_mfma_f32_16x16x32_bf16 v[120:123], v[158:161], v[214:217], v[120:123]
	v_mfma_f32_16x16x32_bf16 v[112:115], v[168:171], v[214:217], v[112:115]
	v_mfma_f32_16x16x32_bf16 v[104:107], v[158:161], v[222:225], v[104:107]
	v_mfma_f32_16x16x32_bf16 v[96:99], v[168:171], v[222:225], v[96:99]
	v_mfma_f32_16x16x32_bf16 v[88:91], v[158:161], v[230:233], v[88:91]
	v_mfma_f32_16x16x32_bf16 v[80:83], v[168:171], v[230:233], v[80:83]
	v_mfma_f32_16x16x32_bf16 v[128:131], v[164:167], v[196:199], v[128:131]
	v_mfma_f32_16x16x32_bf16 v[124:127], v[172:175], v[196:199], v[124:127]
	v_mfma_f32_16x16x32_bf16 v[120:123], v[164:167], v[218:221], v[120:123]
	v_mfma_f32_16x16x32_bf16 v[112:115], v[172:175], v[218:221], v[112:115]
	v_mfma_f32_16x16x32_bf16 v[104:107], v[164:167], v[226:229], v[104:107]
	v_mfma_f32_16x16x32_bf16 v[96:99], v[172:175], v[226:229], v[96:99]
	v_mfma_f32_16x16x32_bf16 v[88:91], v[164:167], v[234:237], v[88:91]
	v_mfma_f32_16x16x32_bf16 v[80:83], v[172:175], v[234:237], v[80:83]
	s_setprio 0
	s_setprio 1
	v_mfma_f32_16x16x32_bf16 v[116:119], v[176:179], v[192:195], v[116:119]
	v_mfma_f32_16x16x32_bf16 v[108:111], v[184:187], v[192:195], v[108:111]
	v_mfma_f32_16x16x32_bf16 v[100:103], v[176:179], v[214:217], v[100:103]
	v_mfma_f32_16x16x32_bf16 v[92:95], v[184:187], v[214:217], v[92:95]
	v_mfma_f32_16x16x32_bf16 v[84:87], v[176:179], v[222:225], v[84:87]
	v_mfma_f32_16x16x32_bf16 v[76:79], v[184:187], v[222:225], v[76:79]
	v_mfma_f32_16x16x32_bf16 v[72:75], v[176:179], v[230:233], v[72:75]
	v_mfma_f32_16x16x32_bf16 v[68:71], v[184:187], v[230:233], v[68:71]
	v_mfma_f32_16x16x32_bf16 v[116:119], v[180:183], v[196:199], v[116:119]
	v_mfma_f32_16x16x32_bf16 v[108:111], v[188:191], v[196:199], v[108:111]
	v_mfma_f32_16x16x32_bf16 v[100:103], v[180:183], v[218:221], v[100:103]
	v_mfma_f32_16x16x32_bf16 v[92:95], v[188:191], v[218:221], v[92:95]
	v_mfma_f32_16x16x32_bf16 v[84:87], v[180:183], v[226:229], v[84:87]
	v_mfma_f32_16x16x32_bf16 v[76:79], v[188:191], v[226:229], v[76:79]
	v_mfma_f32_16x16x32_bf16 v[72:75], v[180:183], v[234:237], v[72:75]
	v_mfma_f32_16x16x32_bf16 v[68:71], v[188:191], v[234:237], v[68:71]
	s_setprio 0
	s_barrier
; #define PG8_STAGE(bufoff, gbase, voff) do { _Pragma("unroll") for (int _i = 0; _i < 2; ++_i) \
;         __builtin_amdgcn_global_load_lds((const unsigned*)((const char*)(gbase) + (voff)[_i]), (LAS unsigned*)(lds + (bufoff) + ldsw + _i * 8192), 16, 0, 0); } while (0)
; #define PG8_LDA(dst, b, h) do { _Pragma("unroll") for (int m = 0; m < 4; ++m) _Pragma("unroll") for (int k = 0; k < 2; ++k) dst[m][k] = *(const LAS bf16x8*)(lds + PG8_SA(b, h) + aoff + m * 2048 + k * 1024); } while (0)
; #define PG8_MMA(ai, bj, At, Bt) do { __builtin_amdgcn_s_setprio(1); _Pragma("unroll") for (int m = 0; m < 4; ++m) _Pragma("unroll") for (int n = 0; n < 2; ++n) _Pragma("unroll") for (int k = 0; k < 2; ++k) \
;         acc[ai][bj][m][n] = __builtin_amdgcn_mfma_f32_16x16x32_bf16(Bt[n][k], At[m][k], acc[ai][bj][m][n], 0, 0, 0); __builtin_amdgcn_s_setprio(0); } while (0)
; #define PG8_WAIT_V(n) asm volatile("s_waitcnt vmcnt(" #n ")" ::: "memory")
; #define PG8_WAIT_L(n) asm volatile("s_waitcnt lgkmcnt(" #n ")" ::: "memory")
; #define PG8_BAR __builtin_amdgcn_s_barrier()
; #define PG8_SCHED __builtin_amdgcn_sched_barrier(0)
;     __device__ __forceinline__ void operator()(const f32x4 (&acc)[2][2][4][2], const Unit& u, int wr, int wc, int fr, int fq) const {
;         if (u.pn < 11) {
; template <class Epi>
; __device__ __forceinline__ void gemm_phase(LAS unsigned char* lds, const Gemm g, const int G, const int cidx, const Epi& E) {
;     ...
;             PG8_LDA(At, 1, 1); PG8_STAGE(PG8_SB(1, 0), b3, voffB); PG8_STAGE(PG8_SB(1, 1), b3 + hstep, voffB); PG8_STAGE(PG8_SA(1, 0), a3, voffA);
;             PG8_WAIT_V(8); PG8_WAIT_L(0); PG8_BAR; PG8_MMA(1, 0, At, B0); PG8_MMA(1, 1, At, B1); PG8_BAR; PG8_SCHED;
;         }
	s_sleep 2
	s_add_i32 s26, s43, s95
	v_lshl_add_u64 v[132:133], v[132:133], 0, s[46:47]
	s_mov_b32 m0, s26
	ds_read_b128 v[192:195], v163 offset:49152
	ds_read_b128 v[196:199], v163 offset:50176
	ds_read_b128 v[214:217], v163 offset:51200
	ds_read_b128 v[218:221], v163 offset:52224
	ds_read_b128 v[222:225], v163 offset:53248
	ds_read_b128 v[226:229], v163 offset:54272
	ds_read_b128 v[230:233], v163 offset:55296
	ds_read_b128 v[234:237], v163 offset:56320
	global_load_lds_dwordx4 v[132:133], off
	s_add_i32 m0, s26, 0x2000
	s_add_u32 s24, s24, 0x40080
	v_lshl_add_u64 v[132:133], v[134:135], 0, s[46:47]
	s_addc_u32 s25, s25, 0
	s_add_i32 s26, s68, s95
	global_load_lds_dwordx4 v[132:133], off
	v_lshl_add_u64 v[132:133], s[24:25], 0, v[148:149]
	s_mov_b32 m0, s26
	s_nop 0
	global_load_lds_dwordx4 v[132:133], off
	v_lshl_add_u64 v[132:133], s[24:25], 0, v[0:1]
	s_add_i32 m0, s26, 0x2000
	s_nop 0
	global_load_lds_dwordx4 v[132:133], off
	v_lshl_add_u64 v[132:133], v[140:141], 0, s[46:47]
	s_mov_b32 m0, s84
	s_nop 0
	global_load_lds_dwordx4 v[132:133], off
	v_lshl_add_u64 v[132:133], v[142:143], 0, s[46:47]
	s_mov_b32 m0, s76
	s_nop 0
	global_load_lds_dwordx4 v[132:133], off
	s_waitcnt vmcnt(8)
	s_waitcnt lgkmcnt(0)
	s_barrier
	s_setprio 1
	s_waitcnt lgkmcnt(0)
	v_mfma_f32_16x16x32_bf16 v[64:67], v[158:161], v[192:195], v[64:67]
	v_mfma_f32_16x16x32_bf16 v[60:63], v[168:171], v[192:195], v[60:63]
	v_mfma_f32_16x16x32_bf16 v[56:59], v[158:161], v[214:217], v[56:59]
	v_mfma_f32_16x16x32_bf16 v[48:51], v[168:171], v[214:217], v[48:51]
	v_mfma_f32_16x16x32_bf16 v[40:43], v[158:161], v[222:225], v[40:43]
	v_mfma_f32_16x16x32_bf16 v[32:35], v[168:171], v[222:225], v[32:35]
	v_mfma_f32_16x16x32_bf16 v[24:27], v[158:161], v[230:233], v[24:27]
	v_mfma_f32_16x16x32_bf16 v[16:19], v[168:171], v[230:233], v[16:19]
	v_mfma_f32_16x16x32_bf16 v[64:67], v[164:167], v[196:199], v[64:67]
	v_mfma_f32_16x16x32_bf16 v[60:63], v[172:175], v[196:199], v[60:63]
	v_mfma_f32_16x16x32_bf16 v[56:59], v[164:167], v[218:221], v[56:59]
	v_mfma_f32_16x16x32_bf16 v[48:51], v[172:175], v[218:221], v[48:51]
	v_mfma_f32_16x16x32_bf16 v[40:43], v[164:167], v[226:229], v[40:43]
	v_mfma_f32_16x16x32_bf16 v[32:35], v[172:175], v[226:229], v[32:35]
	v_mfma_f32_16x16x32_bf16 v[24:27], v[164:167], v[234:237], v[24:27]
	v_mfma_f32_16x16x32_bf16 v[16:19], v[172:175], v[234:237], v[16:19]
	s_setprio 0
	s_setprio 1
	v_mfma_f32_16x16x32_bf16 v[52:55], v[176:179], v[192:195], v[52:55]
	v_mfma_f32_16x16x32_bf16 v[44:47], v[184:187], v[192:195], v[44:47]
	v_mfma_f32_16x16x32_bf16 v[36:39], v[176:179], v[214:217], v[36:39]
	v_mfma_f32_16x16x32_bf16 v[28:31], v[184:187], v[214:217], v[28:31]
	v_mfma_f32_16x16x32_bf16 v[20:23], v[176:179], v[222:225], v[20:23]
	v_mfma_f32_16x16x32_bf16 v[12:15], v[184:187], v[222:225], v[12:15]
	v_mfma_f32_16x16x32_bf16 v[8:11], v[176:179], v[230:233], v[8:11]
	v_mfma_f32_16x16x32_bf16 v[4:7], v[184:187], v[230:233], v[4:7]
	v_mfma_f32_16x16x32_bf16 v[52:55], v[180:183], v[196:199], v[52:55]
	v_mfma_f32_16x16x32_bf16 v[44:47], v[188:191], v[196:199], v[44:47]
	v_mfma_f32_16x16x32_bf16 v[36:39], v[180:183], v[218:221], v[36:39]
	v_mfma_f32_16x16x32_bf16 v[28:31], v[188:191], v[218:221], v[28:31]
	v_mfma_f32_16x16x32_bf16 v[20:23], v[180:183], v[226:229], v[20:23]
	v_mfma_f32_16x16x32_bf16 v[12:15], v[188:191], v[226:229], v[12:15]
	v_mfma_f32_16x16x32_bf16 v[8:11], v[180:183], v[234:237], v[8:11]
	v_mfma_f32_16x16x32_bf16 v[4:7], v[188:191], v[234:237], v[4:7]
	s_setprio 0
	s_barrier
	s_sleep 2
	s_add_i32 s45, s45, 2
	s_add_u32 s42, s42, 0x100
	s_addc_u32 s44, s44, 0
	s_add_u32 s20, s20, 0x100
	s_addc_u32 s21, s21, 0
	s_cmp_gt_u32 s45, 13
	s_cbranch_scc0 .LBB0_601
	s_cmp_gt_i32 s35, 10
	s_mov_b64 s[20:21], -1
	s_mov_b32 s26, 0x1a000
	s_mov_b32 s27, 0x19000
	s_cbranch_scc0 .LBB0_604
; __device__ __forceinline__ unsigned pk2(float lo, float hi) { unsigned r; asm("v_cvt_pk_bf16_f32 %0, %1, %2" : "=v"(r) : "v"(lo), "v"(hi)); return r; }
;     __device__ __forceinline__ void operator()(const f32x4 (&acc)[2][2][4][2], const Unit& u, int wr, int wc, int fr, int fq) const {
;     ...
;             const int g = u.pn - 11, n = g >> 2, q = g & 3;
;             bf16_t* blk = Gt + (((size_t)n * 64 + u.pm) * 8 + q * 2) * 32768 + (size_t)((wr * 4 * 4 + wc) * 64 + fq * 16 + fr) * 8;
; #pragma unroll
;             for (int ai = 0; ai < 2; ++ai)
; #pragma unroll
;                 for (int m = 0; m < 4; ++m)
; #pragma unroll
;                     for (int bj = 0; bj < 2; ++bj) { const f32x4 v0 = acc[ai][bj][m][0], v1 = acc[ai][bj][m][1];
;                         u32x4 w; w.x = pk2(v0[0], v0[1]); w.y = pk2(v0[2], v0[3]); w.z = pk2(v1[0], v1[1]); w.w = pk2(v1[2], v1[3]);
;                         *(u32x4*)(blk + (size_t)bj * 32768 + (size_t)((ai * 8 + m) * 4) * 512) = w; }
	s_add_i32 s9, s35, -11
	s_mov_b32 s21, s77
	s_lshr_b32 s20, s9, 2
	s_ashr_i32 s19, s18, 31
	s_lshl_b64 s[20:21], s[20:21], 9
	s_lshl_b64 s[24:25], s[18:19], 3
	s_add_u32 s11, s20, s24
	s_addc_u32 s21, s21, s25
	s_lshl_b32 s9, s9, 1
	s_and_b32 s9, s9, 6
	s_or_b32 s20, s11, s9
	s_lshl_b64 s[20:21], s[20:21], 16
	v_lshl_add_u64 v[158:159], v[152:153], 0, s[20:21]
	s_mov_b32 s9, 0x11000
	v_add_co_u32_e32 v132, vcc, s9, v158
	v_cvt_pk_bf16_f32 v164, v128, v129
	v_cvt_pk_bf16_f32 v165, v130, v131
	v_cvt_pk_bf16_f32 v166, v124, v125
	v_cvt_pk_bf16_f32 v167, v126, v127
	s_nop 1
	v_addc_co_u32_e32 v133, vcc, 0, v159, vcc
	global_store_dwordx4 v[158:159], v[164:167], off
	v_add_co_u32_e32 v134, vcc, s81, v158
	s_nop 0
	v_cvt_pk_bf16_f32 v164, v116, v117
	v_cvt_pk_bf16_f32 v165, v118, v119
	v_cvt_pk_bf16_f32 v166, v108, v109
	v_cvt_pk_bf16_f32 v167, v110, v111
	global_store_dwordx4 v[132:133], v[164:167], off offset:-4096
	v_addc_co_u32_e32 v135, vcc, 0, v159, vcc
	s_nop 0
	v_cvt_pk_bf16_f32 v164, v120, v121
	v_cvt_pk_bf16_f32 v165, v122, v123
	v_cvt_pk_bf16_f32 v166, v112, v113
	v_cvt_pk_bf16_f32 v167, v114, v115
	s_mov_b32 s9, 0x13000
	global_store_dwordx4 v[134:135], v[164:167], off offset:-4096
	s_mov_b64 s[20:21], 0
	s_nop 0
	v_cvt_pk_bf16_f32 v164, v100, v101
	v_cvt_pk_bf16_f32 v165, v102, v103
	v_cvt_pk_bf16_f32 v166, v92, v93
	v_cvt_pk_bf16_f32 v167, v94, v95
	global_store_dwordx4 v[132:133], v[164:167], off
	v_add_co_u32_e32 v132, vcc, s9, v158
	s_nop 0
	v_cvt_pk_bf16_f32 v164, v104, v105
	v_cvt_pk_bf16_f32 v165, v106, v107
	v_cvt_pk_bf16_f32 v166, v96, v97
	v_cvt_pk_bf16_f32 v167, v98, v99
	s_nop 0
	v_addc_co_u32_e32 v133, vcc, 0, v159, vcc
	global_store_dwordx4 v[134:135], v[164:167], off
	v_add_co_u32_e32 v134, vcc, s82, v158
	s_nop 0
	v_cvt_pk_bf16_f32 v164, v84, v85
	v_cvt_pk_bf16_f32 v165, v86, v87
	v_cvt_pk_bf16_f32 v166, v76, v77
	v_cvt_pk_bf16_f32 v167, v78, v79
	global_store_dwordx4 v[132:133], v[164:167], off offset:-4096
	v_addc_co_u32_e32 v135, vcc, 0, v159, vcc
	s_nop 0
	v_cvt_pk_bf16_f32 v164, v88, v89
	v_cvt_pk_bf16_f32 v165, v90, v91
	v_cvt_pk_bf16_f32 v166, v80, v81
	v_cvt_pk_bf16_f32 v167, v82, v83
	s_mov_b32 s9, 0x9000
	global_store_dwordx4 v[134:135], v[164:167], off
	s_nop 1
	v_cvt_pk_bf16_f32 v164, v72, v73
	v_cvt_pk_bf16_f32 v165, v74, v75
	v_cvt_pk_bf16_f32 v166, v68, v69
	v_cvt_pk_bf16_f32 v167, v70, v71
	global_store_dwordx4 v[132:133], v[164:167], off
	v_add_co_u32_e32 v132, vcc, s9, v158
	s_nop 0
	v_cvt_pk_bf16_f32 v164, v64, v65
	v_cvt_pk_bf16_f32 v165, v66, v67
	v_cvt_pk_bf16_f32 v166, v60, v61
	v_cvt_pk_bf16_f32 v167, v62, v63
	s_nop 0
	v_addc_co_u32_e32 v133, vcc, 0, v159, vcc
	v_add_co_u32_e32 v134, vcc, s27, v158
	global_store_dwordx4 v[132:133], v[164:167], off offset:-4096
	s_nop 0
	v_addc_co_u32_e32 v135, vcc, 0, v159, vcc
	v_cvt_pk_bf16_f32 v164, v52, v53
	v_cvt_pk_bf16_f32 v165, v54, v55
	v_cvt_pk_bf16_f32 v166, v44, v45
	v_cvt_pk_bf16_f32 v167, v46, v47
	s_mov_b32 s9, 0xb000
	global_store_dwordx4 v[134:135], v[164:167], off offset:-4096
	s_nop 1
	v_cvt_pk_bf16_f32 v164, v56, v57
	v_cvt_pk_bf16_f32 v165, v58, v59
	v_cvt_pk_bf16_f32 v166, v48, v49
	v_cvt_pk_bf16_f32 v167, v50, v51
	global_store_dwordx4 v[132:133], v[164:167], off
	v_add_co_u32_e32 v132, vcc, s9, v158
	s_nop 0
	v_cvt_pk_bf16_f32 v164, v36, v37
	v_cvt_pk_bf16_f32 v165, v38, v39
	v_cvt_pk_bf16_f32 v166, v28, v29
	v_cvt_pk_bf16_f32 v167, v30, v31
	s_nop 0
	v_addc_co_u32_e32 v133, vcc, 0, v159, vcc
	global_store_dwordx4 v[134:135], v[164:167], off
	v_add_co_u32_e32 v134, vcc, s26, v158
	s_nop 0
	v_cvt_pk_bf16_f32 v164, v40, v41
	v_cvt_pk_bf16_f32 v165, v42, v43
	v_cvt_pk_bf16_f32 v166, v32, v33
	v_cvt_pk_bf16_f32 v167, v34, v35
	global_store_dwordx4 v[132:133], v[164:167], off offset:-4096
	v_addc_co_u32_e32 v135, vcc, 0, v159, vcc
	s_nop 0
	v_cvt_pk_bf16_f32 v164, v20, v21
	v_cvt_pk_bf16_f32 v165, v22, v23
	v_cvt_pk_bf16_f32 v166, v12, v13
	v_cvt_pk_bf16_f32 v167, v14, v15
	global_store_dwordx4 v[134:135], v[164:167], off
	s_nop 1
	v_cvt_pk_bf16_f32 v164, v24, v25
	v_cvt_pk_bf16_f32 v165, v26, v27
	v_cvt_pk_bf16_f32 v166, v16, v17
	v_cvt_pk_bf16_f32 v167, v18, v19
	global_store_dwordx4 v[132:133], v[164:167], off
	v_add_co_u32_e32 v132, vcc, 0x1b000, v158
	s_nop 0
	v_cvt_pk_bf16_f32 v164, v8, v9
	v_cvt_pk_bf16_f32 v165, v10, v11
	v_cvt_pk_bf16_f32 v166, v4, v5
	v_cvt_pk_bf16_f32 v167, v6, v7
	s_nop 0
	v_addc_co_u32_e32 v133, vcc, 0, v159, vcc
	global_store_dwordx4 v[132:133], v[164:167], off
